# first-layer mixer projection (f32 input residual) and last FFN projection (f32 output) epilogues rewritten with residual loads kept in flight, replacing the per-item dependent waits
# speedup vs baseline: 1.0105x; 1.0078x over previous
; __device__ __forceinline__ unsigned cvt_pk_bf16(float lo, float hi) { unsigned r; asm volatile("v_cvt_pk_bf16_f32 %0, %1, %2" : "=v"(r) : "v"(lo), "v"(hi)); return r; }
;     __device__ __forceinline__ void operator()(f32x4 (&acc)[2][2][4][2], const Unit& u, int wr, int wc, int fr, int fq) const {
;         typedef unsigned u32x2 __attribute__((ext_vector_type(2)));
;         const int row0 = u.pm * BM + wr * 64 + fr, col0 = u.pn * BM + wc * 32 + 4 * fq;
; #pragma unroll
;         for (int ai = 0; ai < 2; ++ai) {
;             float mu[4], rs[4];
; #pragma unroll
;             for (int m = 0; m < 4; ++m) { const f32x2 t = *(const f32x2*)(MUR + 2 * (size_t)(row0 + ai * HALF + m * 16)); mu[m] = t.x; rs[m] = t.y; }
; #pragma unroll
;             for (int bj = 0; bj < 2; ++bj)
; #pragma unroll
;                 for (int n = 0; n < 2; ++n) { const f32x4 g4 = *(const f32x4*)(gp + col0 + bj * HALF + n * 16), b4 = *(const f32x4*)(bp + col0 + bj * HALF + n * 16);
;                     u32x2 told[4];
;                     if (!Xin) {
; #pragma unroll
;                         for (int m = 0; m < 4; ++m) told[m] = *(const u32x2*)(YB + (size_t)(row0 + ai * HALF + m * 16) * 1024 + col0 + bj * HALF + n * 16);
;                     }
; #pragma unroll
;                     for (int m = 0; m < 4; ++m) { const size_t off = (size_t)(row0 + ai * HALF + m * 16) * 1024 + col0 + bj * HALF + n * 16;
;                         f32x4 yo;
;                         if (Xin) yo = *(const f32x4*)(Xin + off);
;                         else { const u32x2 t = told[m]; yo = (f32x4){__uint_as_float(t.x << 16), __uint_as_float(t.x & 0xffff0000u), __uint_as_float(t.y << 16), __uint_as_float(t.y & 0xffff0000u)}; }
;                         const f32x4 yn = ((yo - mu[m]) * rs[m] * g4 + b4) * alpha + acc[ai][bj][m][n];
;                         acc[ai][bj][m][n] = yn;
;                         if (Yout) *(f32x4*)(Yout + off) = yn;
;                         else { u32x2 w; w.x = cvt_pk_bf16(yn[0], yn[1]); w.y = cvt_pk_bf16(yn[2], yn[3]); *(u32x2*)(YB + off) = w; } } } }
.Lres_fastx_a:
	s_lshl_b32 s39, s46, 8
	s_mov_b64 s[4:5], s[26:27]
	s_mov_b64 s[16:17], s[68:69]
	v_add_u32_e32 v223, s39, v171
	v_lshl_or_b32 v222, s48, 8, v248
	v_lshlrev_b32_e32 v221, 3, v223
	v_lshlrev_b32_e32 v212, 2, v222
	v_lshl_add_u32 v220, v223, 12, v212
	v_lshlrev_b32_e32 v212, 1, v222
	v_lshl_add_u32 v223, v223, 11, v212
	v_lshlrev_b32_e32 v222, 2, v222
	global_load_dwordx4 v[128:131], v222, s[22:23] offset:0
	global_load_dwordx4 v[150:153], v222, s[24:25] offset:0
	global_load_dwordx4 v[132:135], v222, s[22:23] offset:64
	global_load_dwordx4 v[154:157], v222, s[24:25] offset:64
	global_load_dwordx4 v[136:139], v222, s[22:23] offset:512
	global_load_dwordx4 v[158:161], v222, s[24:25] offset:512
	global_load_dwordx4 v[146:149], v222, s[22:23] offset:576
	global_load_dwordx4 v[174:177], v222, s[24:25] offset:576
	global_load_dwordx2 v[162:163], v221, s[88:89] offset:0
	global_load_dwordx4 v[180:183], v220, s[4:5] offset:0
	global_load_dwordx4 v[184:187], v220, s[4:5] offset:64
	global_load_dwordx4 v[188:191], v220, s[4:5] offset:512
	global_load_dwordx4 v[192:195], v220, s[4:5] offset:576
	s_add_u32 s4, s4, 0x10000
	s_addc_u32 s5, s5, 0
	global_load_dwordx2 v[178:179], v221, s[88:89] offset:128
	global_load_dwordx4 v[196:199], v220, s[4:5] offset:0
	global_load_dwordx4 v[200:203], v220, s[4:5] offset:64
	global_load_dwordx4 v[204:207], v220, s[4:5] offset:512
	global_load_dwordx4 v[208:211], v220, s[4:5] offset:576
	s_add_u32 s4, s4, 0x10000
	s_addc_u32 s5, s5, 0
	s_waitcnt vmcnt(5)
	v_sub_f32_e32 v180, v180, v162
	v_sub_f32_e32 v181, v181, v162
	v_sub_f32_e32 v182, v182, v162
	v_sub_f32_e32 v183, v183, v162
	v_pk_mul_f32 v[180:181], v[162:163], v[180:181] op_sel:[1,0]
	v_pk_mul_f32 v[182:183], v[162:163], v[182:183] op_sel:[1,0]
	v_pk_fma_f32 v[180:181], v[128:129], v[180:181], v[150:151]
	v_pk_fma_f32 v[182:183], v[130:131], v[182:183], v[152:153]
	v_pk_fma_f32 v[124:125], v[180:181], s[90:91], v[124:125] op_sel_hi:[1,0,1]
	v_pk_fma_f32 v[126:127], v[182:183], s[90:91], v[126:127] op_sel_hi:[1,0,1]
	v_cvt_pk_bf16_f32 v212, v124, v125
	v_cvt_pk_bf16_f32 v213, v126, v127
	global_store_dwordx2 v223, v[212:213], s[16:17] offset:0
	v_sub_f32_e32 v184, v184, v162
	v_sub_f32_e32 v185, v185, v162
	v_sub_f32_e32 v186, v186, v162
	v_sub_f32_e32 v187, v187, v162
	v_pk_mul_f32 v[184:185], v[162:163], v[184:185] op_sel:[1,0]
	v_pk_mul_f32 v[186:187], v[162:163], v[186:187] op_sel:[1,0]
	v_pk_fma_f32 v[184:185], v[132:133], v[184:185], v[154:155]
	v_pk_fma_f32 v[186:187], v[134:135], v[186:187], v[156:157]
	v_pk_fma_f32 v[108:109], v[184:185], s[90:91], v[108:109] op_sel_hi:[1,0,1]
	v_pk_fma_f32 v[110:111], v[186:187], s[90:91], v[110:111] op_sel_hi:[1,0,1]
	v_cvt_pk_bf16_f32 v214, v108, v109
	v_cvt_pk_bf16_f32 v215, v110, v111
	global_store_dwordx2 v223, v[214:215], s[16:17] offset:32
	v_sub_f32_e32 v188, v188, v162
	v_sub_f32_e32 v189, v189, v162
	v_sub_f32_e32 v190, v190, v162
	v_sub_f32_e32 v191, v191, v162
	v_pk_mul_f32 v[188:189], v[162:163], v[188:189] op_sel:[1,0]
	v_pk_mul_f32 v[190:191], v[162:163], v[190:191] op_sel:[1,0]
	v_pk_fma_f32 v[188:189], v[136:137], v[188:189], v[158:159]
	v_pk_fma_f32 v[190:191], v[138:139], v[190:191], v[160:161]
	v_pk_fma_f32 v[92:93], v[188:189], s[90:91], v[92:93] op_sel_hi:[1,0,1]
	v_pk_fma_f32 v[94:95], v[190:191], s[90:91], v[94:95] op_sel_hi:[1,0,1]
	v_cvt_pk_bf16_f32 v212, v92, v93
	v_cvt_pk_bf16_f32 v213, v94, v95
	global_store_dwordx2 v223, v[212:213], s[16:17] offset:256
	v_sub_f32_e32 v192, v192, v162
	v_sub_f32_e32 v193, v193, v162
	v_sub_f32_e32 v194, v194, v162
	v_sub_f32_e32 v195, v195, v162
	v_pk_mul_f32 v[192:193], v[162:163], v[192:193] op_sel:[1,0]
	v_pk_mul_f32 v[194:195], v[162:163], v[194:195] op_sel:[1,0]
	v_pk_fma_f32 v[192:193], v[146:147], v[192:193], v[174:175]
	v_pk_fma_f32 v[194:195], v[148:149], v[194:195], v[176:177]
	v_pk_fma_f32 v[76:77], v[192:193], s[90:91], v[76:77] op_sel_hi:[1,0,1]
	v_pk_fma_f32 v[78:79], v[194:195], s[90:91], v[78:79] op_sel_hi:[1,0,1]
	v_cvt_pk_bf16_f32 v214, v76, v77
	v_cvt_pk_bf16_f32 v215, v78, v79
	global_store_dwordx2 v223, v[214:215], s[16:17] offset:288
	s_add_u32 s16, s16, 0x8000
	s_addc_u32 s17, s17, 0
	global_load_dwordx2 v[162:163], v221, s[88:89] offset:256
	global_load_dwordx4 v[180:183], v220, s[4:5] offset:0
	global_load_dwordx4 v[184:187], v220, s[4:5] offset:64
	global_load_dwordx4 v[188:191], v220, s[4:5] offset:512
	global_load_dwordx4 v[192:195], v220, s[4:5] offset:576
	s_add_u32 s4, s4, 0x10000
	s_addc_u32 s5, s5, 0
	s_waitcnt vmcnt(9)
; __device__ __forceinline__ unsigned cvt_pk_bf16(float lo, float hi) { unsigned r; asm volatile("v_cvt_pk_bf16_f32 %0, %1, %2" : "=v"(r) : "v"(lo), "v"(hi)); return r; }
;     __device__ __forceinline__ void operator()(f32x4 (&acc)[2][2][4][2], const Unit& u, int wr, int wc, int fr, int fq) const {
;     ...
; #pragma unroll
;                     for (int m = 0; m < 4; ++m) { const size_t off = (size_t)(row0 + ai * HALF + m * 16) * 1024 + col0 + bj * HALF + n * 16;
;                         f32x4 yo;
;                         if (Xin) yo = *(const f32x4*)(Xin + off);
;                         else { const u32x2 t = told[m]; yo = (f32x4){__uint_as_float(t.x << 16), __uint_as_float(t.x & 0xffff0000u), __uint_as_float(t.y << 16), __uint_as_float(t.y & 0xffff0000u)}; }
;                         const f32x4 yn = ((yo - mu[m]) * rs[m] * g4 + b4) * alpha + acc[ai][bj][m][n];
;                         acc[ai][bj][m][n] = yn;
;                         if (Yout) *(f32x4*)(Yout + off) = yn;
;                         else { u32x2 w; w.x = cvt_pk_bf16(yn[0], yn[1]); w.y = cvt_pk_bf16(yn[2], yn[3]); *(u32x2*)(YB + off) = w; } } } }
	v_sub_f32_e32 v196, v196, v178
	v_sub_f32_e32 v197, v197, v178
	v_sub_f32_e32 v198, v198, v178
	v_sub_f32_e32 v199, v199, v178
	v_pk_mul_f32 v[196:197], v[178:179], v[196:197] op_sel:[1,0]
	v_pk_mul_f32 v[198:199], v[178:179], v[198:199] op_sel:[1,0]
	v_pk_fma_f32 v[196:197], v[128:129], v[196:197], v[150:151]
	v_pk_fma_f32 v[198:199], v[130:131], v[198:199], v[152:153]
	v_pk_fma_f32 v[120:121], v[196:197], s[90:91], v[120:121] op_sel_hi:[1,0,1]
	v_pk_fma_f32 v[122:123], v[198:199], s[90:91], v[122:123] op_sel_hi:[1,0,1]
	v_cvt_pk_bf16_f32 v212, v120, v121
	v_cvt_pk_bf16_f32 v213, v122, v123
	global_store_dwordx2 v223, v[212:213], s[16:17] offset:0
	v_sub_f32_e32 v200, v200, v178
	v_sub_f32_e32 v201, v201, v178
	v_sub_f32_e32 v202, v202, v178
	v_sub_f32_e32 v203, v203, v178
	v_pk_mul_f32 v[200:201], v[178:179], v[200:201] op_sel:[1,0]
	v_pk_mul_f32 v[202:203], v[178:179], v[202:203] op_sel:[1,0]
	v_pk_fma_f32 v[200:201], v[132:133], v[200:201], v[154:155]
	v_pk_fma_f32 v[202:203], v[134:135], v[202:203], v[156:157]
	v_pk_fma_f32 v[104:105], v[200:201], s[90:91], v[104:105] op_sel_hi:[1,0,1]
	v_pk_fma_f32 v[106:107], v[202:203], s[90:91], v[106:107] op_sel_hi:[1,0,1]
	v_cvt_pk_bf16_f32 v214, v104, v105
	v_cvt_pk_bf16_f32 v215, v106, v107
	global_store_dwordx2 v223, v[214:215], s[16:17] offset:32
	v_sub_f32_e32 v204, v204, v178
	v_sub_f32_e32 v205, v205, v178
	v_sub_f32_e32 v206, v206, v178
	v_sub_f32_e32 v207, v207, v178
	v_pk_mul_f32 v[204:205], v[178:179], v[204:205] op_sel:[1,0]
	v_pk_mul_f32 v[206:207], v[178:179], v[206:207] op_sel:[1,0]
	v_pk_fma_f32 v[204:205], v[136:137], v[204:205], v[158:159]
	v_pk_fma_f32 v[206:207], v[138:139], v[206:207], v[160:161]
	v_pk_fma_f32 v[88:89], v[204:205], s[90:91], v[88:89] op_sel_hi:[1,0,1]
	v_pk_fma_f32 v[90:91], v[206:207], s[90:91], v[90:91] op_sel_hi:[1,0,1]
	v_cvt_pk_bf16_f32 v212, v88, v89
	v_cvt_pk_bf16_f32 v213, v90, v91
	global_store_dwordx2 v223, v[212:213], s[16:17] offset:256
	v_sub_f32_e32 v208, v208, v178
	v_sub_f32_e32 v209, v209, v178
	v_sub_f32_e32 v210, v210, v178
	v_sub_f32_e32 v211, v211, v178
	v_pk_mul_f32 v[208:209], v[178:179], v[208:209] op_sel:[1,0]
	v_pk_mul_f32 v[210:211], v[178:179], v[210:211] op_sel:[1,0]
	v_pk_fma_f32 v[208:209], v[146:147], v[208:209], v[174:175]
	v_pk_fma_f32 v[210:211], v[148:149], v[210:211], v[176:177]
	v_pk_fma_f32 v[72:73], v[208:209], s[90:91], v[72:73] op_sel_hi:[1,0,1]
	v_pk_fma_f32 v[74:75], v[210:211], s[90:91], v[74:75] op_sel_hi:[1,0,1]
	v_cvt_pk_bf16_f32 v214, v72, v73
	v_cvt_pk_bf16_f32 v215, v74, v75
	global_store_dwordx2 v223, v[214:215], s[16:17] offset:288
	s_add_u32 s16, s16, 0x8000
	s_addc_u32 s17, s17, 0
	global_load_dwordx2 v[178:179], v221, s[88:89] offset:384
	global_load_dwordx4 v[196:199], v220, s[4:5] offset:0
	global_load_dwordx4 v[200:203], v220, s[4:5] offset:64
	global_load_dwordx4 v[204:207], v220, s[4:5] offset:512
	global_load_dwordx4 v[208:211], v220, s[4:5] offset:576
	s_add_u32 s4, s4, 0x50000
	s_addc_u32 s5, s5, 0
	s_waitcnt vmcnt(9)
	v_sub_f32_e32 v180, v180, v162
	v_sub_f32_e32 v181, v181, v162
	v_sub_f32_e32 v182, v182, v162
	v_sub_f32_e32 v183, v183, v162
	v_pk_mul_f32 v[180:181], v[162:163], v[180:181] op_sel:[1,0]
	v_pk_mul_f32 v[182:183], v[162:163], v[182:183] op_sel:[1,0]
	v_pk_fma_f32 v[180:181], v[128:129], v[180:181], v[150:151]
	v_pk_fma_f32 v[182:183], v[130:131], v[182:183], v[152:153]
	v_pk_fma_f32 v[116:117], v[180:181], s[90:91], v[116:117] op_sel_hi:[1,0,1]
	v_pk_fma_f32 v[118:119], v[182:183], s[90:91], v[118:119] op_sel_hi:[1,0,1]
	v_cvt_pk_bf16_f32 v212, v116, v117
	v_cvt_pk_bf16_f32 v213, v118, v119
	global_store_dwordx2 v223, v[212:213], s[16:17] offset:0
	v_sub_f32_e32 v184, v184, v162
	v_sub_f32_e32 v185, v185, v162
	v_sub_f32_e32 v186, v186, v162
	v_sub_f32_e32 v187, v187, v162
	v_pk_mul_f32 v[184:185], v[162:163], v[184:185] op_sel:[1,0]
	v_pk_mul_f32 v[186:187], v[162:163], v[186:187] op_sel:[1,0]
	v_pk_fma_f32 v[184:185], v[132:133], v[184:185], v[154:155]
	v_pk_fma_f32 v[186:187], v[134:135], v[186:187], v[156:157]
	v_pk_fma_f32 v[100:101], v[184:185], s[90:91], v[100:101] op_sel_hi:[1,0,1]
	v_pk_fma_f32 v[102:103], v[186:187], s[90:91], v[102:103] op_sel_hi:[1,0,1]
	v_cvt_pk_bf16_f32 v214, v100, v101
	v_cvt_pk_bf16_f32 v215, v102, v103
	global_store_dwordx2 v223, v[214:215], s[16:17] offset:32
	v_sub_f32_e32 v188, v188, v162
	v_sub_f32_e32 v189, v189, v162
	v_sub_f32_e32 v190, v190, v162
	v_sub_f32_e32 v191, v191, v162
	v_pk_mul_f32 v[188:189], v[162:163], v[188:189] op_sel:[1,0]
	v_pk_mul_f32 v[190:191], v[162:163], v[190:191] op_sel:[1,0]
	v_pk_fma_f32 v[188:189], v[136:137], v[188:189], v[158:159]
	v_pk_fma_f32 v[190:191], v[138:139], v[190:191], v[160:161]
	v_pk_fma_f32 v[84:85], v[188:189], s[90:91], v[84:85] op_sel_hi:[1,0,1]
	v_pk_fma_f32 v[86:87], v[190:191], s[90:91], v[86:87] op_sel_hi:[1,0,1]
	v_cvt_pk_bf16_f32 v212, v84, v85
	v_cvt_pk_bf16_f32 v213, v86, v87
	global_store_dwordx2 v223, v[212:213], s[16:17] offset:256
	v_sub_f32_e32 v192, v192, v162
	v_sub_f32_e32 v193, v193, v162
	v_sub_f32_e32 v194, v194, v162
	v_sub_f32_e32 v195, v195, v162
	v_pk_mul_f32 v[192:193], v[162:163], v[192:193] op_sel:[1,0]
	v_pk_mul_f32 v[194:195], v[162:163], v[194:195] op_sel:[1,0]
	v_pk_fma_f32 v[192:193], v[146:147], v[192:193], v[174:175]
	v_pk_fma_f32 v[194:195], v[148:149], v[194:195], v[176:177]
	v_pk_fma_f32 v[68:69], v[192:193], s[90:91], v[68:69] op_sel_hi:[1,0,1]
	v_pk_fma_f32 v[70:71], v[194:195], s[90:91], v[70:71] op_sel_hi:[1,0,1]
	v_cvt_pk_bf16_f32 v214, v68, v69
	v_cvt_pk_bf16_f32 v215, v70, v71
	global_store_dwordx2 v223, v[214:215], s[16:17] offset:288
	s_add_u32 s16, s16, 0x8000
	s_addc_u32 s17, s17, 0
	global_load_dwordx2 v[162:163], v221, s[88:89] offset:1024
	global_load_dwordx4 v[180:183], v220, s[4:5] offset:0
	global_load_dwordx4 v[184:187], v220, s[4:5] offset:64
	global_load_dwordx4 v[188:191], v220, s[4:5] offset:512
	global_load_dwordx4 v[192:195], v220, s[4:5] offset:576
	s_add_u32 s4, s4, 0x10000
	s_addc_u32 s5, s5, 0
	s_waitcnt vmcnt(9)
; __device__ __forceinline__ unsigned cvt_pk_bf16(float lo, float hi) { unsigned r; asm volatile("v_cvt_pk_bf16_f32 %0, %1, %2" : "=v"(r) : "v"(lo), "v"(hi)); return r; }
;     __device__ __forceinline__ void operator()(f32x4 (&acc)[2][2][4][2], const Unit& u, int wr, int wc, int fr, int fq) const {
;     ...
; #pragma unroll
;                     for (int m = 0; m < 4; ++m) { const size_t off = (size_t)(row0 + ai * HALF + m * 16) * 1024 + col0 + bj * HALF + n * 16;
;                         f32x4 yo;
;                         if (Xin) yo = *(const f32x4*)(Xin + off);
;                         else { const u32x2 t = told[m]; yo = (f32x4){__uint_as_float(t.x << 16), __uint_as_float(t.x & 0xffff0000u), __uint_as_float(t.y << 16), __uint_as_float(t.y & 0xffff0000u)}; }
;                         const f32x4 yn = ((yo - mu[m]) * rs[m] * g4 + b4) * alpha + acc[ai][bj][m][n];
;                         acc[ai][bj][m][n] = yn;
;                         if (Yout) *(f32x4*)(Yout + off) = yn;
;                         else { u32x2 w; w.x = cvt_pk_bf16(yn[0], yn[1]); w.y = cvt_pk_bf16(yn[2], yn[3]); *(u32x2*)(YB + off) = w; } } } }
	v_sub_f32_e32 v196, v196, v178
	v_sub_f32_e32 v197, v197, v178
	v_sub_f32_e32 v198, v198, v178
	v_sub_f32_e32 v199, v199, v178
	v_pk_mul_f32 v[196:197], v[178:179], v[196:197] op_sel:[1,0]
	v_pk_mul_f32 v[198:199], v[178:179], v[198:199] op_sel:[1,0]
	v_pk_fma_f32 v[196:197], v[128:129], v[196:197], v[150:151]
	v_pk_fma_f32 v[198:199], v[130:131], v[198:199], v[152:153]
	v_pk_fma_f32 v[112:113], v[196:197], s[90:91], v[112:113] op_sel_hi:[1,0,1]
	v_pk_fma_f32 v[114:115], v[198:199], s[90:91], v[114:115] op_sel_hi:[1,0,1]
	v_cvt_pk_bf16_f32 v212, v112, v113
	v_cvt_pk_bf16_f32 v213, v114, v115
	global_store_dwordx2 v223, v[212:213], s[16:17] offset:0
	v_sub_f32_e32 v200, v200, v178
	v_sub_f32_e32 v201, v201, v178
	v_sub_f32_e32 v202, v202, v178
	v_sub_f32_e32 v203, v203, v178
	v_pk_mul_f32 v[200:201], v[178:179], v[200:201] op_sel:[1,0]
	v_pk_mul_f32 v[202:203], v[178:179], v[202:203] op_sel:[1,0]
	v_pk_fma_f32 v[200:201], v[132:133], v[200:201], v[154:155]
	v_pk_fma_f32 v[202:203], v[134:135], v[202:203], v[156:157]
	v_pk_fma_f32 v[96:97], v[200:201], s[90:91], v[96:97] op_sel_hi:[1,0,1]
	v_pk_fma_f32 v[98:99], v[202:203], s[90:91], v[98:99] op_sel_hi:[1,0,1]
	v_cvt_pk_bf16_f32 v214, v96, v97
	v_cvt_pk_bf16_f32 v215, v98, v99
	global_store_dwordx2 v223, v[214:215], s[16:17] offset:32
	v_sub_f32_e32 v204, v204, v178
	v_sub_f32_e32 v205, v205, v178
	v_sub_f32_e32 v206, v206, v178
	v_sub_f32_e32 v207, v207, v178
	v_pk_mul_f32 v[204:205], v[178:179], v[204:205] op_sel:[1,0]
	v_pk_mul_f32 v[206:207], v[178:179], v[206:207] op_sel:[1,0]
	v_pk_fma_f32 v[204:205], v[136:137], v[204:205], v[158:159]
	v_pk_fma_f32 v[206:207], v[138:139], v[206:207], v[160:161]
	v_pk_fma_f32 v[80:81], v[204:205], s[90:91], v[80:81] op_sel_hi:[1,0,1]
	v_pk_fma_f32 v[82:83], v[206:207], s[90:91], v[82:83] op_sel_hi:[1,0,1]
	v_cvt_pk_bf16_f32 v212, v80, v81
	v_cvt_pk_bf16_f32 v213, v82, v83
	global_store_dwordx2 v223, v[212:213], s[16:17] offset:256
	v_sub_f32_e32 v208, v208, v178
	v_sub_f32_e32 v209, v209, v178
	v_sub_f32_e32 v210, v210, v178
	v_sub_f32_e32 v211, v211, v178
	v_pk_mul_f32 v[208:209], v[178:179], v[208:209] op_sel:[1,0]
	v_pk_mul_f32 v[210:211], v[178:179], v[210:211] op_sel:[1,0]
	v_pk_fma_f32 v[208:209], v[146:147], v[208:209], v[174:175]
	v_pk_fma_f32 v[210:211], v[148:149], v[210:211], v[176:177]
	v_pk_fma_f32 v[64:65], v[208:209], s[90:91], v[64:65] op_sel_hi:[1,0,1]
	v_pk_fma_f32 v[66:67], v[210:211], s[90:91], v[66:67] op_sel_hi:[1,0,1]
	v_cvt_pk_bf16_f32 v214, v64, v65
	v_cvt_pk_bf16_f32 v215, v66, v67
	global_store_dwordx2 v223, v[214:215], s[16:17] offset:288
	s_add_u32 s16, s16, 0x28000
	s_addc_u32 s17, s17, 0
	global_load_dwordx2 v[178:179], v221, s[88:89] offset:1152
	global_load_dwordx4 v[196:199], v220, s[4:5] offset:0
	global_load_dwordx4 v[200:203], v220, s[4:5] offset:64
	global_load_dwordx4 v[204:207], v220, s[4:5] offset:512
	global_load_dwordx4 v[208:211], v220, s[4:5] offset:576
	s_add_u32 s4, s4, 0x10000
	s_addc_u32 s5, s5, 0
	s_waitcnt vmcnt(9)
	v_sub_f32_e32 v180, v180, v162
	v_sub_f32_e32 v181, v181, v162
	v_sub_f32_e32 v182, v182, v162
	v_sub_f32_e32 v183, v183, v162
	v_pk_mul_f32 v[180:181], v[162:163], v[180:181] op_sel:[1,0]
	v_pk_mul_f32 v[182:183], v[162:163], v[182:183] op_sel:[1,0]
	v_pk_fma_f32 v[180:181], v[128:129], v[180:181], v[150:151]
	v_pk_fma_f32 v[182:183], v[130:131], v[182:183], v[152:153]
	v_pk_fma_f32 v[60:61], v[180:181], s[90:91], v[60:61] op_sel_hi:[1,0,1]
	v_pk_fma_f32 v[62:63], v[182:183], s[90:91], v[62:63] op_sel_hi:[1,0,1]
	v_cvt_pk_bf16_f32 v212, v60, v61
	v_cvt_pk_bf16_f32 v213, v62, v63
	global_store_dwordx2 v223, v[212:213], s[16:17] offset:0
	v_sub_f32_e32 v184, v184, v162
	v_sub_f32_e32 v185, v185, v162
	v_sub_f32_e32 v186, v186, v162
	v_sub_f32_e32 v187, v187, v162
	v_pk_mul_f32 v[184:185], v[162:163], v[184:185] op_sel:[1,0]
	v_pk_mul_f32 v[186:187], v[162:163], v[186:187] op_sel:[1,0]
	v_pk_fma_f32 v[184:185], v[132:133], v[184:185], v[154:155]
	v_pk_fma_f32 v[186:187], v[134:135], v[186:187], v[156:157]
	v_pk_fma_f32 v[44:45], v[184:185], s[90:91], v[44:45] op_sel_hi:[1,0,1]
	v_pk_fma_f32 v[46:47], v[186:187], s[90:91], v[46:47] op_sel_hi:[1,0,1]
	v_cvt_pk_bf16_f32 v214, v44, v45
	v_cvt_pk_bf16_f32 v215, v46, v47
	global_store_dwordx2 v223, v[214:215], s[16:17] offset:32
	v_sub_f32_e32 v188, v188, v162
	v_sub_f32_e32 v189, v189, v162
	v_sub_f32_e32 v190, v190, v162
	v_sub_f32_e32 v191, v191, v162
	v_pk_mul_f32 v[188:189], v[162:163], v[188:189] op_sel:[1,0]
	v_pk_mul_f32 v[190:191], v[162:163], v[190:191] op_sel:[1,0]
	v_pk_fma_f32 v[188:189], v[136:137], v[188:189], v[158:159]
	v_pk_fma_f32 v[190:191], v[138:139], v[190:191], v[160:161]
	v_pk_fma_f32 v[28:29], v[188:189], s[90:91], v[28:29] op_sel_hi:[1,0,1]
	v_pk_fma_f32 v[30:31], v[190:191], s[90:91], v[30:31] op_sel_hi:[1,0,1]
	v_cvt_pk_bf16_f32 v212, v28, v29
	v_cvt_pk_bf16_f32 v213, v30, v31
	global_store_dwordx2 v223, v[212:213], s[16:17] offset:256
	v_sub_f32_e32 v192, v192, v162
	v_sub_f32_e32 v193, v193, v162
	v_sub_f32_e32 v194, v194, v162
	v_sub_f32_e32 v195, v195, v162
	v_pk_mul_f32 v[192:193], v[162:163], v[192:193] op_sel:[1,0]
	v_pk_mul_f32 v[194:195], v[162:163], v[194:195] op_sel:[1,0]
	v_pk_fma_f32 v[192:193], v[146:147], v[192:193], v[174:175]
	v_pk_fma_f32 v[194:195], v[148:149], v[194:195], v[176:177]
	v_pk_fma_f32 v[12:13], v[192:193], s[90:91], v[12:13] op_sel_hi:[1,0,1]
	v_pk_fma_f32 v[14:15], v[194:195], s[90:91], v[14:15] op_sel_hi:[1,0,1]
	v_cvt_pk_bf16_f32 v214, v12, v13
	v_cvt_pk_bf16_f32 v215, v14, v15
	global_store_dwordx2 v223, v[214:215], s[16:17] offset:288
	s_add_u32 s16, s16, 0x8000
	s_addc_u32 s17, s17, 0
	global_load_dwordx2 v[162:163], v221, s[88:89] offset:1280
	global_load_dwordx4 v[180:183], v220, s[4:5] offset:0
	global_load_dwordx4 v[184:187], v220, s[4:5] offset:64
	global_load_dwordx4 v[188:191], v220, s[4:5] offset:512
	global_load_dwordx4 v[192:195], v220, s[4:5] offset:576
	s_add_u32 s4, s4, 0x10000
	s_addc_u32 s5, s5, 0
	s_waitcnt vmcnt(9)
; __device__ __forceinline__ unsigned cvt_pk_bf16(float lo, float hi) { unsigned r; asm volatile("v_cvt_pk_bf16_f32 %0, %1, %2" : "=v"(r) : "v"(lo), "v"(hi)); return r; }
;     __device__ __forceinline__ void operator()(f32x4 (&acc)[2][2][4][2], const Unit& u, int wr, int wc, int fr, int fq) const {
;     ...
; #pragma unroll
;                     for (int m = 0; m < 4; ++m) { const size_t off = (size_t)(row0 + ai * HALF + m * 16) * 1024 + col0 + bj * HALF + n * 16;
;                         f32x4 yo;
;                         if (Xin) yo = *(const f32x4*)(Xin + off);
;                         else { const u32x2 t = told[m]; yo = (f32x4){__uint_as_float(t.x << 16), __uint_as_float(t.x & 0xffff0000u), __uint_as_float(t.y << 16), __uint_as_float(t.y & 0xffff0000u)}; }
;                         const f32x4 yn = ((yo - mu[m]) * rs[m] * g4 + b4) * alpha + acc[ai][bj][m][n];
;                         acc[ai][bj][m][n] = yn;
;                         if (Yout) *(f32x4*)(Yout + off) = yn;
;                         else { u32x2 w; w.x = cvt_pk_bf16(yn[0], yn[1]); w.y = cvt_pk_bf16(yn[2], yn[3]); *(u32x2*)(YB + off) = w; } } } }
	v_sub_f32_e32 v196, v196, v178
	v_sub_f32_e32 v197, v197, v178
	v_sub_f32_e32 v198, v198, v178
	v_sub_f32_e32 v199, v199, v178
	v_pk_mul_f32 v[196:197], v[178:179], v[196:197] op_sel:[1,0]
	v_pk_mul_f32 v[198:199], v[178:179], v[198:199] op_sel:[1,0]
	v_pk_fma_f32 v[196:197], v[128:129], v[196:197], v[150:151]
	v_pk_fma_f32 v[198:199], v[130:131], v[198:199], v[152:153]
	v_pk_fma_f32 v[56:57], v[196:197], s[90:91], v[56:57] op_sel_hi:[1,0,1]
	v_pk_fma_f32 v[58:59], v[198:199], s[90:91], v[58:59] op_sel_hi:[1,0,1]
	v_cvt_pk_bf16_f32 v212, v56, v57
	v_cvt_pk_bf16_f32 v213, v58, v59
	global_store_dwordx2 v223, v[212:213], s[16:17] offset:0
	v_sub_f32_e32 v200, v200, v178
	v_sub_f32_e32 v201, v201, v178
	v_sub_f32_e32 v202, v202, v178
	v_sub_f32_e32 v203, v203, v178
	v_pk_mul_f32 v[200:201], v[178:179], v[200:201] op_sel:[1,0]
	v_pk_mul_f32 v[202:203], v[178:179], v[202:203] op_sel:[1,0]
	v_pk_fma_f32 v[200:201], v[132:133], v[200:201], v[154:155]
	v_pk_fma_f32 v[202:203], v[134:135], v[202:203], v[156:157]
	v_pk_fma_f32 v[40:41], v[200:201], s[90:91], v[40:41] op_sel_hi:[1,0,1]
	v_pk_fma_f32 v[42:43], v[202:203], s[90:91], v[42:43] op_sel_hi:[1,0,1]
	v_cvt_pk_bf16_f32 v214, v40, v41
	v_cvt_pk_bf16_f32 v215, v42, v43
	global_store_dwordx2 v223, v[214:215], s[16:17] offset:32
	v_sub_f32_e32 v204, v204, v178
	v_sub_f32_e32 v205, v205, v178
	v_sub_f32_e32 v206, v206, v178
	v_sub_f32_e32 v207, v207, v178
	v_pk_mul_f32 v[204:205], v[178:179], v[204:205] op_sel:[1,0]
	v_pk_mul_f32 v[206:207], v[178:179], v[206:207] op_sel:[1,0]
	v_pk_fma_f32 v[204:205], v[136:137], v[204:205], v[158:159]
	v_pk_fma_f32 v[206:207], v[138:139], v[206:207], v[160:161]
	v_pk_fma_f32 v[24:25], v[204:205], s[90:91], v[24:25] op_sel_hi:[1,0,1]
	v_pk_fma_f32 v[26:27], v[206:207], s[90:91], v[26:27] op_sel_hi:[1,0,1]
	v_cvt_pk_bf16_f32 v212, v24, v25
	v_cvt_pk_bf16_f32 v213, v26, v27
	global_store_dwordx2 v223, v[212:213], s[16:17] offset:256
	v_sub_f32_e32 v208, v208, v178
	v_sub_f32_e32 v209, v209, v178
	v_sub_f32_e32 v210, v210, v178
	v_sub_f32_e32 v211, v211, v178
	v_pk_mul_f32 v[208:209], v[178:179], v[208:209] op_sel:[1,0]
	v_pk_mul_f32 v[210:211], v[178:179], v[210:211] op_sel:[1,0]
	v_pk_fma_f32 v[208:209], v[146:147], v[208:209], v[174:175]
	v_pk_fma_f32 v[210:211], v[148:149], v[210:211], v[176:177]
	v_pk_fma_f32 v[8:9], v[208:209], s[90:91], v[8:9] op_sel_hi:[1,0,1]
	v_pk_fma_f32 v[10:11], v[210:211], s[90:91], v[10:11] op_sel_hi:[1,0,1]
	v_cvt_pk_bf16_f32 v214, v8, v9
	v_cvt_pk_bf16_f32 v215, v10, v11
	global_store_dwordx2 v223, v[214:215], s[16:17] offset:288
	s_add_u32 s16, s16, 0x8000
	s_addc_u32 s17, s17, 0
	global_load_dwordx2 v[178:179], v221, s[88:89] offset:1408
	global_load_dwordx4 v[196:199], v220, s[4:5] offset:0
	global_load_dwordx4 v[200:203], v220, s[4:5] offset:64
	global_load_dwordx4 v[204:207], v220, s[4:5] offset:512
	global_load_dwordx4 v[208:211], v220, s[4:5] offset:576
	s_waitcnt vmcnt(9)
	v_sub_f32_e32 v180, v180, v162
	v_sub_f32_e32 v181, v181, v162
	v_sub_f32_e32 v182, v182, v162
	v_sub_f32_e32 v183, v183, v162
	v_pk_mul_f32 v[180:181], v[162:163], v[180:181] op_sel:[1,0]
	v_pk_mul_f32 v[182:183], v[162:163], v[182:183] op_sel:[1,0]
	v_pk_fma_f32 v[180:181], v[128:129], v[180:181], v[150:151]
	v_pk_fma_f32 v[182:183], v[130:131], v[182:183], v[152:153]
	v_pk_fma_f32 v[52:53], v[180:181], s[90:91], v[52:53] op_sel_hi:[1,0,1]
	v_pk_fma_f32 v[54:55], v[182:183], s[90:91], v[54:55] op_sel_hi:[1,0,1]
	v_cvt_pk_bf16_f32 v212, v52, v53
	v_cvt_pk_bf16_f32 v213, v54, v55
	global_store_dwordx2 v223, v[212:213], s[16:17] offset:0
	v_sub_f32_e32 v184, v184, v162
	v_sub_f32_e32 v185, v185, v162
	v_sub_f32_e32 v186, v186, v162
	v_sub_f32_e32 v187, v187, v162
	v_pk_mul_f32 v[184:185], v[162:163], v[184:185] op_sel:[1,0]
	v_pk_mul_f32 v[186:187], v[162:163], v[186:187] op_sel:[1,0]
	v_pk_fma_f32 v[184:185], v[132:133], v[184:185], v[154:155]
	v_pk_fma_f32 v[186:187], v[134:135], v[186:187], v[156:157]
	v_pk_fma_f32 v[36:37], v[184:185], s[90:91], v[36:37] op_sel_hi:[1,0,1]
	v_pk_fma_f32 v[38:39], v[186:187], s[90:91], v[38:39] op_sel_hi:[1,0,1]
	v_cvt_pk_bf16_f32 v214, v36, v37
	v_cvt_pk_bf16_f32 v215, v38, v39
	global_store_dwordx2 v223, v[214:215], s[16:17] offset:32
	v_sub_f32_e32 v188, v188, v162
	v_sub_f32_e32 v189, v189, v162
	v_sub_f32_e32 v190, v190, v162
	v_sub_f32_e32 v191, v191, v162
	v_pk_mul_f32 v[188:189], v[162:163], v[188:189] op_sel:[1,0]
	v_pk_mul_f32 v[190:191], v[162:163], v[190:191] op_sel:[1,0]
	v_pk_fma_f32 v[188:189], v[136:137], v[188:189], v[158:159]
	v_pk_fma_f32 v[190:191], v[138:139], v[190:191], v[160:161]
	v_pk_fma_f32 v[20:21], v[188:189], s[90:91], v[20:21] op_sel_hi:[1,0,1]
	v_pk_fma_f32 v[22:23], v[190:191], s[90:91], v[22:23] op_sel_hi:[1,0,1]
	v_cvt_pk_bf16_f32 v212, v20, v21
	v_cvt_pk_bf16_f32 v213, v22, v23
	global_store_dwordx2 v223, v[212:213], s[16:17] offset:256
	v_sub_f32_e32 v192, v192, v162
	v_sub_f32_e32 v193, v193, v162
	v_sub_f32_e32 v194, v194, v162
	v_sub_f32_e32 v195, v195, v162
	v_pk_mul_f32 v[192:193], v[162:163], v[192:193] op_sel:[1,0]
	v_pk_mul_f32 v[194:195], v[162:163], v[194:195] op_sel:[1,0]
	v_pk_fma_f32 v[192:193], v[146:147], v[192:193], v[174:175]
	v_pk_fma_f32 v[194:195], v[148:149], v[194:195], v[176:177]
	v_pk_fma_f32 v[4:5], v[192:193], s[90:91], v[4:5] op_sel_hi:[1,0,1]
	v_pk_fma_f32 v[6:7], v[194:195], s[90:91], v[6:7] op_sel_hi:[1,0,1]
	v_cvt_pk_bf16_f32 v214, v4, v5
	v_cvt_pk_bf16_f32 v215, v6, v7
	global_store_dwordx2 v223, v[214:215], s[16:17] offset:288
	s_add_u32 s16, s16, 0x8000
	s_addc_u32 s17, s17, 0
	s_waitcnt vmcnt(4)
; #define PG8_LAS __attribute__((address_space(3)))
; __device__ __forceinline__ unsigned cvt_pk_bf16(float lo, float hi) { unsigned r; asm volatile("v_cvt_pk_bf16_f32 %0, %1, %2" : "=v"(r) : "v"(lo), "v"(hi)); return r; }
;     __device__ __forceinline__ void operator()(f32x4 (&acc)[2][2][4][2], const Unit& u, int wr, int wc, int fr, int fq) const {
;     ...
;                     for (int m = 0; m < 4; ++m) { const size_t off = (size_t)(row0 + ai * HALF + m * 16) * 1024 + col0 + bj * HALF + n * 16;
;                         f32x4 yo;
;                         if (Xin) yo = *(const f32x4*)(Xin + off);
;                         else { const u32x2 t = told[m]; yo = (f32x4){__uint_as_float(t.x << 16), __uint_as_float(t.x & 0xffff0000u), __uint_as_float(t.y << 16), __uint_as_float(t.y & 0xffff0000u)}; }
;                         const f32x4 yn = ((yo - mu[m]) * rs[m] * g4 + b4) * alpha + acc[ai][bj][m][n];
;                         acc[ai][bj][m][n] = yn;
;                         if (Yout) *(f32x4*)(Yout + off) = yn;
;                         else { u32x2 w; w.x = cvt_pk_bf16(yn[0], yn[1]); w.y = cvt_pk_bf16(yn[2], yn[3]); *(u32x2*)(YB + off) = w; } } } }
;         PG8_LAS f32x2* P = (PG8_LAS f32x2*)(lds + 131072);
; #pragma unroll
;         for (int ai = 0; ai < 2; ++ai)
; #pragma unroll
;             for (int m = 0; m < 4; ++m) {
;                 float s = 0.f;
; #pragma unroll
;                 for (int bj = 0; bj < 2; ++bj)
; #pragma unroll
;                     for (int n = 0; n < 2; ++n) { const f32x4 x = acc[ai][bj][m][n]; s += (x[0] + x[1]) + (x[2] + x[3]); }
;                 s += __shfl_xor(s, 16); s += __shfl_xor(s, 32);
	v_sub_f32_e32 v196, v196, v178
	v_sub_f32_e32 v197, v197, v178
	v_sub_f32_e32 v198, v198, v178
	v_sub_f32_e32 v199, v199, v178
	v_pk_mul_f32 v[196:197], v[178:179], v[196:197] op_sel:[1,0]
	v_pk_mul_f32 v[198:199], v[178:179], v[198:199] op_sel:[1,0]
	v_pk_fma_f32 v[196:197], v[128:129], v[196:197], v[150:151]
	v_pk_fma_f32 v[198:199], v[130:131], v[198:199], v[152:153]
	v_pk_fma_f32 v[48:49], v[196:197], s[90:91], v[48:49] op_sel_hi:[1,0,1]
	v_pk_fma_f32 v[50:51], v[198:199], s[90:91], v[50:51] op_sel_hi:[1,0,1]
	v_cvt_pk_bf16_f32 v212, v48, v49
	v_cvt_pk_bf16_f32 v213, v50, v51
	global_store_dwordx2 v223, v[212:213], s[16:17] offset:0
	v_sub_f32_e32 v200, v200, v178
	v_sub_f32_e32 v201, v201, v178
	v_sub_f32_e32 v202, v202, v178
	v_sub_f32_e32 v203, v203, v178
	v_pk_mul_f32 v[200:201], v[178:179], v[200:201] op_sel:[1,0]
	v_pk_mul_f32 v[202:203], v[178:179], v[202:203] op_sel:[1,0]
	v_pk_fma_f32 v[200:201], v[132:133], v[200:201], v[154:155]
	v_pk_fma_f32 v[202:203], v[134:135], v[202:203], v[156:157]
	v_pk_fma_f32 v[32:33], v[200:201], s[90:91], v[32:33] op_sel_hi:[1,0,1]
	v_pk_fma_f32 v[34:35], v[202:203], s[90:91], v[34:35] op_sel_hi:[1,0,1]
	v_cvt_pk_bf16_f32 v214, v32, v33
	v_cvt_pk_bf16_f32 v215, v34, v35
	global_store_dwordx2 v223, v[214:215], s[16:17] offset:32
	v_sub_f32_e32 v204, v204, v178
	v_sub_f32_e32 v205, v205, v178
	v_sub_f32_e32 v206, v206, v178
	v_sub_f32_e32 v207, v207, v178
	v_pk_mul_f32 v[204:205], v[178:179], v[204:205] op_sel:[1,0]
	v_pk_mul_f32 v[206:207], v[178:179], v[206:207] op_sel:[1,0]
	v_pk_fma_f32 v[204:205], v[136:137], v[204:205], v[158:159]
	v_pk_fma_f32 v[206:207], v[138:139], v[206:207], v[160:161]
	v_pk_fma_f32 v[16:17], v[204:205], s[90:91], v[16:17] op_sel_hi:[1,0,1]
	v_pk_fma_f32 v[18:19], v[206:207], s[90:91], v[18:19] op_sel_hi:[1,0,1]
	v_cvt_pk_bf16_f32 v212, v16, v17
	v_cvt_pk_bf16_f32 v213, v18, v19
	global_store_dwordx2 v223, v[212:213], s[16:17] offset:256
	v_sub_f32_e32 v208, v208, v178
	v_sub_f32_e32 v209, v209, v178
	v_sub_f32_e32 v210, v210, v178
	v_sub_f32_e32 v211, v211, v178
	v_pk_mul_f32 v[208:209], v[178:179], v[208:209] op_sel:[1,0]
	v_pk_mul_f32 v[210:211], v[178:179], v[210:211] op_sel:[1,0]
	v_pk_fma_f32 v[208:209], v[146:147], v[208:209], v[174:175]
	v_pk_fma_f32 v[210:211], v[148:149], v[210:211], v[176:177]
	v_pk_fma_f32 v[0:1], v[208:209], s[90:91], v[0:1] op_sel_hi:[1,0,1]
	v_pk_fma_f32 v[2:3], v[210:211], s[90:91], v[2:3] op_sel_hi:[1,0,1]
	v_cvt_pk_bf16_f32 v214, v0, v1
	v_cvt_pk_bf16_f32 v215, v2, v3
	global_store_dwordx2 v223, v[214:215], s[16:17] offset:288
	v_xor_b32_e32 v205, 16, v230
	v_xor_b32_e32 v204, 32, v230
	v_lshlrev_b32_e32 v205, 2, v205
	v_lshlrev_b32_e32 v204, 2, v204
	v_add_f32_e32 v207, v124, v125
	v_add_f32_e32 v206, v126, v127
	v_add_f32_e32 v223, v207, v206
	v_add_f32_e32 v207, v108, v109
	v_add_f32_e32 v206, v110, v111
	v_add_f32_e32 v207, v207, v206
	v_add_f32_e32 v223, v223, v207
	v_add_f32_e32 v207, v92, v93
	v_add_f32_e32 v206, v94, v95
	v_add_f32_e32 v207, v207, v206
	v_add_f32_e32 v223, v223, v207
	v_add_f32_e32 v207, v76, v77
	v_add_f32_e32 v206, v78, v79
	v_add_f32_e32 v207, v207, v206
	v_add_f32_e32 v223, v223, v207
	v_add_f32_e32 v207, v120, v121
	v_add_f32_e32 v206, v122, v123
	v_add_f32_e32 v222, v207, v206
	v_add_f32_e32 v207, v104, v105
	v_add_f32_e32 v206, v106, v107
	v_add_f32_e32 v207, v207, v206
	v_add_f32_e32 v222, v222, v207
	v_add_f32_e32 v207, v88, v89
	v_add_f32_e32 v206, v90, v91
	v_add_f32_e32 v207, v207, v206
	v_add_f32_e32 v222, v222, v207
	v_add_f32_e32 v207, v72, v73
	v_add_f32_e32 v206, v74, v75
	v_add_f32_e32 v207, v207, v206
	v_add_f32_e32 v222, v222, v207
	v_add_f32_e32 v207, v116, v117
	v_add_f32_e32 v206, v118, v119
	v_add_f32_e32 v221, v207, v206
	v_add_f32_e32 v207, v100, v101
	v_add_f32_e32 v206, v102, v103
	v_add_f32_e32 v207, v207, v206
	v_add_f32_e32 v221, v221, v207
	v_add_f32_e32 v207, v84, v85
	v_add_f32_e32 v206, v86, v87
	v_add_f32_e32 v207, v207, v206
	v_add_f32_e32 v221, v221, v207
	v_add_f32_e32 v207, v68, v69
	v_add_f32_e32 v206, v70, v71
	v_add_f32_e32 v207, v207, v206
	v_add_f32_e32 v221, v221, v207
	v_add_f32_e32 v207, v112, v113
	v_add_f32_e32 v206, v114, v115
	v_add_f32_e32 v220, v207, v206
	v_add_f32_e32 v207, v96, v97
	v_add_f32_e32 v206, v98, v99
	v_add_f32_e32 v207, v207, v206
	v_add_f32_e32 v220, v220, v207
	v_add_f32_e32 v207, v80, v81
	v_add_f32_e32 v206, v82, v83
	v_add_f32_e32 v207, v207, v206
	v_add_f32_e32 v220, v220, v207
	v_add_f32_e32 v207, v64, v65
	v_add_f32_e32 v206, v66, v67
	v_add_f32_e32 v207, v207, v206
	v_add_f32_e32 v220, v220, v207
	v_add_f32_e32 v207, v60, v61
	v_add_f32_e32 v206, v62, v63
	v_add_f32_e32 v219, v207, v206
	v_add_f32_e32 v207, v44, v45
	v_add_f32_e32 v206, v46, v47
	v_add_f32_e32 v207, v207, v206
	v_add_f32_e32 v219, v219, v207
	v_add_f32_e32 v207, v28, v29
	v_add_f32_e32 v206, v30, v31
	v_add_f32_e32 v207, v207, v206
	v_add_f32_e32 v219, v219, v207
	v_add_f32_e32 v207, v12, v13
	v_add_f32_e32 v206, v14, v15
	v_add_f32_e32 v207, v207, v206
	v_add_f32_e32 v219, v219, v207
	v_add_f32_e32 v207, v56, v57
	v_add_f32_e32 v206, v58, v59
	v_add_f32_e32 v218, v207, v206
	v_add_f32_e32 v207, v40, v41
	v_add_f32_e32 v206, v42, v43
	v_add_f32_e32 v207, v207, v206
	v_add_f32_e32 v218, v218, v207
	v_add_f32_e32 v207, v24, v25
	v_add_f32_e32 v206, v26, v27
	v_add_f32_e32 v207, v207, v206
	v_add_f32_e32 v218, v218, v207
	v_add_f32_e32 v207, v8, v9
	v_add_f32_e32 v206, v10, v11
	v_add_f32_e32 v207, v207, v206
	v_add_f32_e32 v218, v218, v207
	v_add_f32_e32 v207, v52, v53
	v_add_f32_e32 v206, v54, v55
	v_add_f32_e32 v217, v207, v206
	v_add_f32_e32 v207, v36, v37
	v_add_f32_e32 v206, v38, v39
	v_add_f32_e32 v207, v207, v206
	v_add_f32_e32 v217, v217, v207
	v_add_f32_e32 v207, v20, v21
	v_add_f32_e32 v206, v22, v23
	v_add_f32_e32 v207, v207, v206
	v_add_f32_e32 v217, v217, v207
	v_add_f32_e32 v207, v4, v5
	v_add_f32_e32 v206, v6, v7
	v_add_f32_e32 v207, v207, v206
	v_add_f32_e32 v217, v217, v207
	v_add_f32_e32 v207, v48, v49
	v_add_f32_e32 v206, v50, v51
	v_add_f32_e32 v216, v207, v206
	v_add_f32_e32 v207, v32, v33
	v_add_f32_e32 v206, v34, v35
	v_add_f32_e32 v207, v207, v206
	v_add_f32_e32 v216, v216, v207
	v_add_f32_e32 v207, v16, v17
	v_add_f32_e32 v206, v18, v19
	v_add_f32_e32 v207, v207, v206
	v_add_f32_e32 v216, v216, v207
	v_add_f32_e32 v207, v0, v1
	v_add_f32_e32 v206, v2, v3
	v_add_f32_e32 v207, v207, v206
	v_add_f32_e32 v216, v216, v207
	ds_bpermute_b32 v215, v205, v223
	ds_bpermute_b32 v214, v205, v222
	ds_bpermute_b32 v213, v205, v221
	ds_bpermute_b32 v212, v205, v220
	ds_bpermute_b32 v211, v205, v219
	ds_bpermute_b32 v210, v205, v218
	ds_bpermute_b32 v209, v205, v217
	ds_bpermute_b32 v208, v205, v216
	s_waitcnt lgkmcnt(0)
;     __device__ __forceinline__ void operator()(f32x4 (&acc)[2][2][4][2], const Unit& u, int wr, int wc, int fr, int fq) const {
;     ...
;                 s += __shfl_xor(s, 16); s += __shfl_xor(s, 32);
;                 const float mw = s * (1.0f / 64.0f); float q = 0.f;
; #pragma unroll
;                 for (int bj = 0; bj < 2; ++bj)
; #pragma unroll
;                     for (int n = 0; n < 2; ++n) { const f32x4 d = acc[ai][bj][m][n] - mw; q += (d[0] * d[0] + d[1] * d[1]) + (d[2] * d[2] + d[3] * d[3]); }
	v_add_f32_e32 v223, v223, v215
	v_add_f32_e32 v222, v222, v214
	v_add_f32_e32 v221, v221, v213
	v_add_f32_e32 v220, v220, v212
	v_add_f32_e32 v219, v219, v211
	v_add_f32_e32 v218, v218, v210
	v_add_f32_e32 v217, v217, v209
	v_add_f32_e32 v216, v216, v208
	ds_bpermute_b32 v215, v204, v223
	ds_bpermute_b32 v214, v204, v222
	ds_bpermute_b32 v213, v204, v221
	ds_bpermute_b32 v212, v204, v220
	ds_bpermute_b32 v211, v204, v219
	ds_bpermute_b32 v210, v204, v218
	ds_bpermute_b32 v209, v204, v217
	ds_bpermute_b32 v208, v204, v216
	s_waitcnt lgkmcnt(0)
	v_add_f32_e32 v223, v223, v215
	v_add_f32_e32 v222, v222, v214
	v_add_f32_e32 v221, v221, v213
	v_add_f32_e32 v220, v220, v212
	v_add_f32_e32 v219, v219, v211
	v_add_f32_e32 v218, v218, v210
	v_add_f32_e32 v217, v217, v209
	v_add_f32_e32 v216, v216, v208
	v_fmac_f32_e32 v124, 0xbc800000, v223
	v_fmac_f32_e32 v125, 0xbc800000, v223
	v_fmac_f32_e32 v126, 0xbc800000, v223
	v_fmac_f32_e32 v127, 0xbc800000, v223
	v_mul_f32_e32 v207, v125, v125
	v_fmac_f32_e32 v207, v124, v124
	v_mul_f32_e32 v206, v127, v127
	v_fmac_f32_e32 v206, v126, v126
	v_add_f32_e32 v129, v207, v206
	v_fmac_f32_e32 v108, 0xbc800000, v223
	v_fmac_f32_e32 v109, 0xbc800000, v223
	v_fmac_f32_e32 v110, 0xbc800000, v223
	v_fmac_f32_e32 v111, 0xbc800000, v223
	v_mul_f32_e32 v207, v109, v109
	v_fmac_f32_e32 v207, v108, v108
	v_mul_f32_e32 v206, v111, v111
	v_fmac_f32_e32 v206, v110, v110
	v_add_f32_e32 v207, v207, v206
	v_add_f32_e32 v129, v129, v207
	v_fmac_f32_e32 v92, 0xbc800000, v223
	v_fmac_f32_e32 v93, 0xbc800000, v223
	v_fmac_f32_e32 v94, 0xbc800000, v223
	v_fmac_f32_e32 v95, 0xbc800000, v223
	v_mul_f32_e32 v207, v93, v93
	v_fmac_f32_e32 v207, v92, v92
	v_mul_f32_e32 v206, v95, v95
	v_fmac_f32_e32 v206, v94, v94
	v_add_f32_e32 v207, v207, v206
	v_add_f32_e32 v129, v129, v207
	v_fmac_f32_e32 v76, 0xbc800000, v223
	v_fmac_f32_e32 v77, 0xbc800000, v223
	v_fmac_f32_e32 v78, 0xbc800000, v223
	v_fmac_f32_e32 v79, 0xbc800000, v223
	v_mul_f32_e32 v207, v77, v77
	v_fmac_f32_e32 v207, v76, v76
	v_mul_f32_e32 v206, v79, v79
	v_fmac_f32_e32 v206, v78, v78
	v_add_f32_e32 v207, v207, v206
	v_add_f32_e32 v129, v129, v207
	v_fmac_f32_e32 v120, 0xbc800000, v222
	v_fmac_f32_e32 v121, 0xbc800000, v222
	v_fmac_f32_e32 v122, 0xbc800000, v222
	v_fmac_f32_e32 v123, 0xbc800000, v222
	v_mul_f32_e32 v207, v121, v121
	v_fmac_f32_e32 v207, v120, v120
	v_mul_f32_e32 v206, v123, v123
	v_fmac_f32_e32 v206, v122, v122
	v_add_f32_e32 v131, v207, v206
	v_fmac_f32_e32 v104, 0xbc800000, v222
	v_fmac_f32_e32 v105, 0xbc800000, v222
	v_fmac_f32_e32 v106, 0xbc800000, v222
	v_fmac_f32_e32 v107, 0xbc800000, v222
	v_mul_f32_e32 v207, v105, v105
	v_fmac_f32_e32 v207, v104, v104
	v_mul_f32_e32 v206, v107, v107
	v_fmac_f32_e32 v206, v106, v106
	v_add_f32_e32 v207, v207, v206
	v_add_f32_e32 v131, v131, v207
	v_fmac_f32_e32 v88, 0xbc800000, v222
	v_fmac_f32_e32 v89, 0xbc800000, v222
	v_fmac_f32_e32 v90, 0xbc800000, v222
	v_fmac_f32_e32 v91, 0xbc800000, v222
	v_mul_f32_e32 v207, v89, v89
	v_fmac_f32_e32 v207, v88, v88
	v_mul_f32_e32 v206, v91, v91
	v_fmac_f32_e32 v206, v90, v90
	v_add_f32_e32 v207, v207, v206
	v_add_f32_e32 v131, v131, v207
	v_fmac_f32_e32 v72, 0xbc800000, v222
	v_fmac_f32_e32 v73, 0xbc800000, v222
	v_fmac_f32_e32 v74, 0xbc800000, v222
	v_fmac_f32_e32 v75, 0xbc800000, v222
	v_mul_f32_e32 v207, v73, v73
	v_fmac_f32_e32 v207, v72, v72
	v_mul_f32_e32 v206, v75, v75
	v_fmac_f32_e32 v206, v74, v74
	v_add_f32_e32 v207, v207, v206
	v_add_f32_e32 v131, v131, v207
	v_fmac_f32_e32 v116, 0xbc800000, v221
	v_fmac_f32_e32 v117, 0xbc800000, v221
	v_fmac_f32_e32 v118, 0xbc800000, v221
	v_fmac_f32_e32 v119, 0xbc800000, v221
	v_mul_f32_e32 v207, v117, v117
	v_fmac_f32_e32 v207, v116, v116
	v_mul_f32_e32 v206, v119, v119
	v_fmac_f32_e32 v206, v118, v118
	v_add_f32_e32 v133, v207, v206
	v_fmac_f32_e32 v100, 0xbc800000, v221
	v_fmac_f32_e32 v101, 0xbc800000, v221
	v_fmac_f32_e32 v102, 0xbc800000, v221
	v_fmac_f32_e32 v103, 0xbc800000, v221
	v_mul_f32_e32 v207, v101, v101
	v_fmac_f32_e32 v207, v100, v100
	v_mul_f32_e32 v206, v103, v103
	v_fmac_f32_e32 v206, v102, v102
	v_add_f32_e32 v207, v207, v206
	v_add_f32_e32 v133, v133, v207
	v_fmac_f32_e32 v84, 0xbc800000, v221
	v_fmac_f32_e32 v85, 0xbc800000, v221
	v_fmac_f32_e32 v86, 0xbc800000, v221
	v_fmac_f32_e32 v87, 0xbc800000, v221
	v_mul_f32_e32 v207, v85, v85
	v_fmac_f32_e32 v207, v84, v84
	v_mul_f32_e32 v206, v87, v87
	v_fmac_f32_e32 v206, v86, v86
	v_add_f32_e32 v207, v207, v206
	v_add_f32_e32 v133, v133, v207
	v_fmac_f32_e32 v68, 0xbc800000, v221
	v_fmac_f32_e32 v69, 0xbc800000, v221
	v_fmac_f32_e32 v70, 0xbc800000, v221
	v_fmac_f32_e32 v71, 0xbc800000, v221
	v_mul_f32_e32 v207, v69, v69
	v_fmac_f32_e32 v207, v68, v68
	v_mul_f32_e32 v206, v71, v71
	v_fmac_f32_e32 v206, v70, v70
	v_add_f32_e32 v207, v207, v206
	v_add_f32_e32 v133, v133, v207
	v_fmac_f32_e32 v112, 0xbc800000, v220
	v_fmac_f32_e32 v113, 0xbc800000, v220
	v_fmac_f32_e32 v114, 0xbc800000, v220
	v_fmac_f32_e32 v115, 0xbc800000, v220
	v_mul_f32_e32 v207, v113, v113
	v_fmac_f32_e32 v207, v112, v112
	v_mul_f32_e32 v206, v115, v115
	v_fmac_f32_e32 v206, v114, v114
	v_add_f32_e32 v135, v207, v206
	v_fmac_f32_e32 v96, 0xbc800000, v220
	v_fmac_f32_e32 v97, 0xbc800000, v220
	v_fmac_f32_e32 v98, 0xbc800000, v220
	v_fmac_f32_e32 v99, 0xbc800000, v220
	v_mul_f32_e32 v207, v97, v97
	v_fmac_f32_e32 v207, v96, v96
	v_mul_f32_e32 v206, v99, v99
	v_fmac_f32_e32 v206, v98, v98
	v_add_f32_e32 v207, v207, v206
	v_add_f32_e32 v135, v135, v207
	v_fmac_f32_e32 v80, 0xbc800000, v220
	v_fmac_f32_e32 v81, 0xbc800000, v220
	v_fmac_f32_e32 v82, 0xbc800000, v220
	v_fmac_f32_e32 v83, 0xbc800000, v220
;     __device__ __forceinline__ void operator()(f32x4 (&acc)[2][2][4][2], const Unit& u, int wr, int wc, int fr, int fq) const {
;     ...
; #pragma unroll
;                 for (int bj = 0; bj < 2; ++bj)
; #pragma unroll
;                     for (int n = 0; n < 2; ++n) { const f32x4 d = acc[ai][bj][m][n] - mw; q += (d[0] * d[0] + d[1] * d[1]) + (d[2] * d[2] + d[3] * d[3]); }
;                 q += __shfl_xor(q, 16); q += __shfl_xor(q, 32);
	v_mul_f32_e32 v207, v81, v81
	v_fmac_f32_e32 v207, v80, v80
	v_mul_f32_e32 v206, v83, v83
	v_fmac_f32_e32 v206, v82, v82
	v_add_f32_e32 v207, v207, v206
	v_add_f32_e32 v135, v135, v207
	v_fmac_f32_e32 v64, 0xbc800000, v220
	v_fmac_f32_e32 v65, 0xbc800000, v220
	v_fmac_f32_e32 v66, 0xbc800000, v220
	v_fmac_f32_e32 v67, 0xbc800000, v220
	v_mul_f32_e32 v207, v65, v65
	v_fmac_f32_e32 v207, v64, v64
	v_mul_f32_e32 v206, v67, v67
	v_fmac_f32_e32 v206, v66, v66
	v_add_f32_e32 v207, v207, v206
	v_add_f32_e32 v135, v135, v207
	v_fmac_f32_e32 v60, 0xbc800000, v219
	v_fmac_f32_e32 v61, 0xbc800000, v219
	v_fmac_f32_e32 v62, 0xbc800000, v219
	v_fmac_f32_e32 v63, 0xbc800000, v219
	v_mul_f32_e32 v207, v61, v61
	v_fmac_f32_e32 v207, v60, v60
	v_mul_f32_e32 v206, v63, v63
	v_fmac_f32_e32 v206, v62, v62
	v_add_f32_e32 v137, v207, v206
	v_fmac_f32_e32 v44, 0xbc800000, v219
	v_fmac_f32_e32 v45, 0xbc800000, v219
	v_fmac_f32_e32 v46, 0xbc800000, v219
	v_fmac_f32_e32 v47, 0xbc800000, v219
	v_mul_f32_e32 v207, v45, v45
	v_fmac_f32_e32 v207, v44, v44
	v_mul_f32_e32 v206, v47, v47
	v_fmac_f32_e32 v206, v46, v46
	v_add_f32_e32 v207, v207, v206
	v_add_f32_e32 v137, v137, v207
	v_fmac_f32_e32 v28, 0xbc800000, v219
	v_fmac_f32_e32 v29, 0xbc800000, v219
	v_fmac_f32_e32 v30, 0xbc800000, v219
	v_fmac_f32_e32 v31, 0xbc800000, v219
	v_mul_f32_e32 v207, v29, v29
	v_fmac_f32_e32 v207, v28, v28
	v_mul_f32_e32 v206, v31, v31
	v_fmac_f32_e32 v206, v30, v30
	v_add_f32_e32 v207, v207, v206
	v_add_f32_e32 v137, v137, v207
	v_fmac_f32_e32 v12, 0xbc800000, v219
	v_fmac_f32_e32 v13, 0xbc800000, v219
	v_fmac_f32_e32 v14, 0xbc800000, v219
	v_fmac_f32_e32 v15, 0xbc800000, v219
	v_mul_f32_e32 v207, v13, v13
	v_fmac_f32_e32 v207, v12, v12
	v_mul_f32_e32 v206, v15, v15
	v_fmac_f32_e32 v206, v14, v14
	v_add_f32_e32 v207, v207, v206
	v_add_f32_e32 v137, v137, v207
	v_fmac_f32_e32 v56, 0xbc800000, v218
	v_fmac_f32_e32 v57, 0xbc800000, v218
	v_fmac_f32_e32 v58, 0xbc800000, v218
	v_fmac_f32_e32 v59, 0xbc800000, v218
	v_mul_f32_e32 v207, v57, v57
	v_fmac_f32_e32 v207, v56, v56
	v_mul_f32_e32 v206, v59, v59
	v_fmac_f32_e32 v206, v58, v58
	v_add_f32_e32 v139, v207, v206
	v_fmac_f32_e32 v40, 0xbc800000, v218
	v_fmac_f32_e32 v41, 0xbc800000, v218
	v_fmac_f32_e32 v42, 0xbc800000, v218
	v_fmac_f32_e32 v43, 0xbc800000, v218
	v_mul_f32_e32 v207, v41, v41
	v_fmac_f32_e32 v207, v40, v40
	v_mul_f32_e32 v206, v43, v43
	v_fmac_f32_e32 v206, v42, v42
	v_add_f32_e32 v207, v207, v206
	v_add_f32_e32 v139, v139, v207
	v_fmac_f32_e32 v24, 0xbc800000, v218
	v_fmac_f32_e32 v25, 0xbc800000, v218
	v_fmac_f32_e32 v26, 0xbc800000, v218
	v_fmac_f32_e32 v27, 0xbc800000, v218
	v_mul_f32_e32 v207, v25, v25
	v_fmac_f32_e32 v207, v24, v24
	v_mul_f32_e32 v206, v27, v27
	v_fmac_f32_e32 v206, v26, v26
	v_add_f32_e32 v207, v207, v206
	v_add_f32_e32 v139, v139, v207
	v_fmac_f32_e32 v8, 0xbc800000, v218
	v_fmac_f32_e32 v9, 0xbc800000, v218
	v_fmac_f32_e32 v10, 0xbc800000, v218
	v_fmac_f32_e32 v11, 0xbc800000, v218
	v_mul_f32_e32 v207, v9, v9
	v_fmac_f32_e32 v207, v8, v8
	v_mul_f32_e32 v206, v11, v11
	v_fmac_f32_e32 v206, v10, v10
	v_add_f32_e32 v207, v207, v206
	v_add_f32_e32 v139, v139, v207
	v_fmac_f32_e32 v52, 0xbc800000, v217
	v_fmac_f32_e32 v53, 0xbc800000, v217
	v_fmac_f32_e32 v54, 0xbc800000, v217
	v_fmac_f32_e32 v55, 0xbc800000, v217
	v_mul_f32_e32 v207, v53, v53
	v_fmac_f32_e32 v207, v52, v52
	v_mul_f32_e32 v206, v55, v55
	v_fmac_f32_e32 v206, v54, v54
	v_add_f32_e32 v147, v207, v206
	v_fmac_f32_e32 v36, 0xbc800000, v217
	v_fmac_f32_e32 v37, 0xbc800000, v217
	v_fmac_f32_e32 v38, 0xbc800000, v217
	v_fmac_f32_e32 v39, 0xbc800000, v217
	v_mul_f32_e32 v207, v37, v37
	v_fmac_f32_e32 v207, v36, v36
	v_mul_f32_e32 v206, v39, v39
	v_fmac_f32_e32 v206, v38, v38
	v_add_f32_e32 v207, v207, v206
	v_add_f32_e32 v147, v147, v207
	v_fmac_f32_e32 v20, 0xbc800000, v217
	v_fmac_f32_e32 v21, 0xbc800000, v217
	v_fmac_f32_e32 v22, 0xbc800000, v217
	v_fmac_f32_e32 v23, 0xbc800000, v217
	v_mul_f32_e32 v207, v21, v21
	v_fmac_f32_e32 v207, v20, v20
	v_mul_f32_e32 v206, v23, v23
	v_fmac_f32_e32 v206, v22, v22
	v_add_f32_e32 v207, v207, v206
	v_add_f32_e32 v147, v147, v207
	v_fmac_f32_e32 v4, 0xbc800000, v217
	v_fmac_f32_e32 v5, 0xbc800000, v217
	v_fmac_f32_e32 v6, 0xbc800000, v217
	v_fmac_f32_e32 v7, 0xbc800000, v217
	v_mul_f32_e32 v207, v5, v5
	v_fmac_f32_e32 v207, v4, v4
	v_mul_f32_e32 v206, v7, v7
	v_fmac_f32_e32 v206, v6, v6
	v_add_f32_e32 v207, v207, v206
	v_add_f32_e32 v147, v147, v207
	v_fmac_f32_e32 v48, 0xbc800000, v216
	v_fmac_f32_e32 v49, 0xbc800000, v216
	v_fmac_f32_e32 v50, 0xbc800000, v216
	v_fmac_f32_e32 v51, 0xbc800000, v216
	v_mul_f32_e32 v207, v49, v49
	v_fmac_f32_e32 v207, v48, v48
	v_mul_f32_e32 v206, v51, v51
	v_fmac_f32_e32 v206, v50, v50
	v_add_f32_e32 v149, v207, v206
	v_fmac_f32_e32 v32, 0xbc800000, v216
	v_fmac_f32_e32 v33, 0xbc800000, v216
	v_fmac_f32_e32 v34, 0xbc800000, v216
	v_fmac_f32_e32 v35, 0xbc800000, v216
	v_mul_f32_e32 v207, v33, v33
	v_fmac_f32_e32 v207, v32, v32
	v_mul_f32_e32 v206, v35, v35
	v_fmac_f32_e32 v206, v34, v34
	v_add_f32_e32 v207, v207, v206
	v_add_f32_e32 v149, v149, v207
	v_fmac_f32_e32 v16, 0xbc800000, v216
	v_fmac_f32_e32 v17, 0xbc800000, v216
	v_fmac_f32_e32 v18, 0xbc800000, v216
	v_fmac_f32_e32 v19, 0xbc800000, v216
	v_mul_f32_e32 v207, v17, v17
	v_fmac_f32_e32 v207, v16, v16
	v_mul_f32_e32 v206, v19, v19
	v_fmac_f32_e32 v206, v18, v18
	v_add_f32_e32 v207, v207, v206
	v_add_f32_e32 v149, v149, v207
	v_fmac_f32_e32 v0, 0xbc800000, v216
	v_fmac_f32_e32 v1, 0xbc800000, v216
	v_fmac_f32_e32 v2, 0xbc800000, v216
	v_fmac_f32_e32 v3, 0xbc800000, v216
	v_mul_f32_e32 v207, v1, v1
	v_fmac_f32_e32 v207, v0, v0
	v_mul_f32_e32 v206, v3, v3
	v_fmac_f32_e32 v206, v2, v2
	v_add_f32_e32 v207, v207, v206
	v_add_f32_e32 v149, v149, v207
	ds_bpermute_b32 v215, v205, v129
	ds_bpermute_b32 v214, v205, v131
	ds_bpermute_b32 v213, v205, v133
	ds_bpermute_b32 v212, v205, v135
	ds_bpermute_b32 v211, v205, v137
	ds_bpermute_b32 v210, v205, v139
	ds_bpermute_b32 v209, v205, v147
	ds_bpermute_b32 v208, v205, v149
	s_waitcnt lgkmcnt(0)
;     __device__ __forceinline__ void operator()(f32x4 (&acc)[2][2][4][2], const Unit& u, int wr, int wc, int fr, int fq) const {
;     ...
;                 q += __shfl_xor(q, 16); q += __shfl_xor(q, 32);
;                 if (fq == 0) P[(ai * HALF + wr * 64 + m * 16 + fr) * 4 + wc] = (f32x2){mw, q};
	v_add_f32_e32 v129, v129, v215
	v_add_f32_e32 v131, v131, v214
	v_add_f32_e32 v133, v133, v213
	v_add_f32_e32 v135, v135, v212
	v_add_f32_e32 v137, v137, v211
	v_add_f32_e32 v139, v139, v210
	v_add_f32_e32 v147, v147, v209
	v_add_f32_e32 v149, v149, v208
	ds_bpermute_b32 v215, v204, v129
	ds_bpermute_b32 v214, v204, v131
	ds_bpermute_b32 v213, v204, v133
	ds_bpermute_b32 v212, v204, v135
	ds_bpermute_b32 v211, v204, v137
	ds_bpermute_b32 v210, v204, v139
	ds_bpermute_b32 v209, v204, v147
	ds_bpermute_b32 v208, v204, v149
	s_waitcnt lgkmcnt(0)
	v_add_f32_e32 v129, v129, v215
	v_add_f32_e32 v131, v131, v214
	v_add_f32_e32 v133, v133, v213
	v_add_f32_e32 v135, v135, v212
	v_add_f32_e32 v137, v137, v211
	v_add_f32_e32 v139, v139, v210
	v_add_f32_e32 v147, v147, v209
	v_add_f32_e32 v149, v149, v208
	v_mul_f32_e32 v128, 0x3c800000, v223
	v_mul_f32_e32 v130, 0x3c800000, v222
	v_mul_f32_e32 v132, 0x3c800000, v221
	v_mul_f32_e32 v134, 0x3c800000, v220
	v_mul_f32_e32 v136, 0x3c800000, v219
	v_mul_f32_e32 v138, 0x3c800000, v218
	v_mul_f32_e32 v146, 0x3c800000, v217
	v_mul_f32_e32 v148, 0x3c800000, v216
	s_and_saveexec_b64 s[4:5], s[8:9]
	ds_write_b64 v234, v[128:129]
	ds_write_b64 v234, v[130:131] offset:512
	ds_write_b64 v234, v[132:133] offset:1024
	ds_write_b64 v234, v[134:135] offset:1536
	ds_write_b64 v234, v[136:137] offset:4096
	ds_write_b64 v234, v[138:139] offset:4608
	ds_write_b64 v234, v[146:147] offset:5120
	ds_write_b64 v234, v[148:149] offset:5632
	s_or_b64 exec, exec, s[4:5]
	s_branch .Lres_join_a

; __device__ __forceinline__ unsigned cvt_pk_bf16(float lo, float hi) { unsigned r; asm volatile("v_cvt_pk_bf16_f32 %0, %1, %2" : "=v"(r) : "v"(lo), "v"(hi)); return r; }
;     __device__ __forceinline__ void operator()(f32x4 (&acc)[2][2][4][2], const Unit& u, int wr, int wc, int fr, int fq) const {
;     ...
;                 for (int n = 0; n < 2; ++n) { const f32x4 g4 = *(const f32x4*)(gp + col0 + bj * HALF + n * 16), b4 = *(const f32x4*)(bp + col0 + bj * HALF + n * 16);
;                     u32x2 told[4];
;                     if (!Xin) {
; #pragma unroll
;                         for (int m = 0; m < 4; ++m) told[m] = *(const u32x2*)(YB + (size_t)(row0 + ai * HALF + m * 16) * 1024 + col0 + bj * HALF + n * 16);
;                     }
; #pragma unroll
;                     for (int m = 0; m < 4; ++m) { const size_t off = (size_t)(row0 + ai * HALF + m * 16) * 1024 + col0 + bj * HALF + n * 16;
;                         f32x4 yo;
;                         if (Xin) yo = *(const f32x4*)(Xin + off);
;                         else { const u32x2 t = told[m]; yo = (f32x4){__uint_as_float(t.x << 16), __uint_as_float(t.x & 0xffff0000u), __uint_as_float(t.y << 16), __uint_as_float(t.y & 0xffff0000u)}; }
;                         const f32x4 yn = ((yo - mu[m]) * rs[m] * g4 + b4) * alpha + acc[ai][bj][m][n];
;                         acc[ai][bj][m][n] = yn;
;                         if (Yout) *(f32x4*)(Yout + off) = yn;
;                         else { u32x2 w; w.x = cvt_pk_bf16(yn[0], yn[1]); w.y = cvt_pk_bf16(yn[2], yn[3]); *(u32x2*)(YB + off) = w; } } } }
.Lres_fasty_b:
	s_lshl_b32 s36, s30, 8
	s_mov_b64 s[4:5], s[68:69]
	s_mov_b64 s[16:17], s[52:53]
	v_add_u32_e32 v219, s36, v171
	v_lshl_or_b32 v223, s34, 8, v215
	v_lshlrev_b32_e32 v222, 3, v219
	v_lshlrev_b32_e32 v206, 2, v223
	v_lshl_add_u32 v221, v219, 12, v206
	v_lshlrev_b32_e32 v206, 1, v223
	v_lshl_add_u32 v219, v219, 11, v206
	v_lshlrev_b32_e32 v223, 2, v223
	global_load_dwordx4 v[128:131], v223, s[20:21] offset:0
	global_load_dwordx4 v[150:153], v223, s[22:23] offset:0
	global_load_dwordx4 v[132:135], v223, s[20:21] offset:64
	global_load_dwordx4 v[154:157], v223, s[22:23] offset:64
	global_load_dwordx4 v[142:145], v223, s[20:21] offset:512
	global_load_dwordx4 v[158:161], v223, s[22:23] offset:512
	global_load_dwordx4 v[146:149], v223, s[20:21] offset:576
	global_load_dwordx4 v[174:177], v223, s[22:23] offset:576
	global_load_dwordx2 v[162:163], v222, s[88:89] offset:0
	global_load_dwordx2 v[182:183], v219, s[4:5] offset:0
	global_load_dwordx2 v[184:185], v219, s[4:5] offset:32
	global_load_dwordx2 v[186:187], v219, s[4:5] offset:256
	global_load_dwordx2 v[188:189], v219, s[4:5] offset:288
	s_add_u32 s4, s4, 0x8000
	s_addc_u32 s5, s5, 0
	global_load_dwordx2 v[178:179], v222, s[88:89] offset:128
	global_load_dwordx2 v[190:191], v219, s[4:5] offset:0
	global_load_dwordx2 v[192:193], v219, s[4:5] offset:32
	global_load_dwordx2 v[194:195], v219, s[4:5] offset:256
	global_load_dwordx2 v[196:197], v219, s[4:5] offset:288
	s_add_u32 s4, s4, 0x8000
	s_addc_u32 s5, s5, 0
	global_load_dwordx2 v[180:181], v222, s[88:89] offset:256
	global_load_dwordx2 v[198:199], v219, s[4:5] offset:0
	global_load_dwordx2 v[200:201], v219, s[4:5] offset:32
	global_load_dwordx2 v[202:203], v219, s[4:5] offset:256
	global_load_dwordx2 v[204:205], v219, s[4:5] offset:288
	s_add_u32 s4, s4, 0x8000
	s_addc_u32 s5, s5, 0
	s_waitcnt vmcnt(10)
	v_lshlrev_b32_e32 v206, 16, v182
	v_and_b32_e32 v207, 0xffff0000, v182
	v_lshlrev_b32_e32 v182, 16, v183
	v_and_b32_e32 v183, 0xffff0000, v183
	v_sub_f32_e32 v206, v206, v162
	v_sub_f32_e32 v207, v207, v162
	v_sub_f32_e32 v182, v182, v162
	v_sub_f32_e32 v183, v183, v162
	v_pk_mul_f32 v[206:207], v[162:163], v[206:207] op_sel:[1,0]
	v_pk_mul_f32 v[182:183], v[162:163], v[182:183] op_sel:[1,0]
	v_pk_fma_f32 v[206:207], v[128:129], v[206:207], v[150:151]
	v_pk_fma_f32 v[182:183], v[130:131], v[182:183], v[152:153]
	v_pk_fma_f32 v[60:61], v[206:207], s[90:91], v[60:61] op_sel_hi:[1,0,1]
	v_pk_fma_f32 v[62:63], v[182:183], s[90:91], v[62:63] op_sel_hi:[1,0,1]
	global_store_dwordx4 v221, v[60:63], s[16:17] offset:0
	v_lshlrev_b32_e32 v208, 16, v184
	v_and_b32_e32 v209, 0xffff0000, v184
	v_lshlrev_b32_e32 v184, 16, v185
	v_and_b32_e32 v185, 0xffff0000, v185
	v_sub_f32_e32 v208, v208, v162
	v_sub_f32_e32 v209, v209, v162
	v_sub_f32_e32 v184, v184, v162
	v_sub_f32_e32 v185, v185, v162
	v_pk_mul_f32 v[208:209], v[162:163], v[208:209] op_sel:[1,0]
	v_pk_mul_f32 v[184:185], v[162:163], v[184:185] op_sel:[1,0]
	v_pk_fma_f32 v[208:209], v[132:133], v[208:209], v[154:155]
	v_pk_fma_f32 v[184:185], v[134:135], v[184:185], v[156:157]
	v_pk_fma_f32 v[92:93], v[208:209], s[90:91], v[92:93] op_sel_hi:[1,0,1]
	v_pk_fma_f32 v[94:95], v[184:185], s[90:91], v[94:95] op_sel_hi:[1,0,1]
	global_store_dwordx4 v221, v[92:95], s[16:17] offset:64
	v_lshlrev_b32_e32 v206, 16, v186
	v_and_b32_e32 v207, 0xffff0000, v186
	v_lshlrev_b32_e32 v186, 16, v187
	v_and_b32_e32 v187, 0xffff0000, v187
	v_sub_f32_e32 v206, v206, v162
	v_sub_f32_e32 v207, v207, v162
	v_sub_f32_e32 v186, v186, v162
	v_sub_f32_e32 v187, v187, v162
	v_pk_mul_f32 v[206:207], v[162:163], v[206:207] op_sel:[1,0]
	v_pk_mul_f32 v[186:187], v[162:163], v[186:187] op_sel:[1,0]
	v_pk_fma_f32 v[206:207], v[142:143], v[206:207], v[158:159]
	v_pk_fma_f32 v[186:187], v[144:145], v[186:187], v[160:161]
	v_pk_fma_f32 v[120:121], v[206:207], s[90:91], v[120:121] op_sel_hi:[1,0,1]
	v_pk_fma_f32 v[122:123], v[186:187], s[90:91], v[122:123] op_sel_hi:[1,0,1]
	global_store_dwordx4 v221, v[120:123], s[16:17] offset:512
	v_lshlrev_b32_e32 v208, 16, v188
	v_and_b32_e32 v209, 0xffff0000, v188
	v_lshlrev_b32_e32 v188, 16, v189
	v_and_b32_e32 v189, 0xffff0000, v189
	v_sub_f32_e32 v208, v208, v162
	v_sub_f32_e32 v209, v209, v162
	v_sub_f32_e32 v188, v188, v162
	v_sub_f32_e32 v189, v189, v162
	v_pk_mul_f32 v[208:209], v[162:163], v[208:209] op_sel:[1,0]
	v_pk_mul_f32 v[188:189], v[162:163], v[188:189] op_sel:[1,0]
	v_pk_fma_f32 v[208:209], v[146:147], v[208:209], v[174:175]
	v_pk_fma_f32 v[188:189], v[148:149], v[188:189], v[176:177]
	v_pk_fma_f32 v[124:125], v[208:209], s[90:91], v[124:125] op_sel_hi:[1,0,1]
	v_pk_fma_f32 v[126:127], v[188:189], s[90:91], v[126:127] op_sel_hi:[1,0,1]
	global_store_dwordx4 v221, v[124:127], s[16:17] offset:576
	s_add_u32 s16, s16, 0x10000
	s_addc_u32 s17, s17, 0
	global_load_dwordx2 v[162:163], v222, s[88:89] offset:384
	global_load_dwordx2 v[182:183], v219, s[4:5] offset:0
	global_load_dwordx2 v[184:185], v219, s[4:5] offset:32
	global_load_dwordx2 v[186:187], v219, s[4:5] offset:256
	global_load_dwordx2 v[188:189], v219, s[4:5] offset:288
	s_add_u32 s4, s4, 0x28000
	s_addc_u32 s5, s5, 0
	s_waitcnt vmcnt(14)
; __device__ __forceinline__ unsigned cvt_pk_bf16(float lo, float hi) { unsigned r; asm volatile("v_cvt_pk_bf16_f32 %0, %1, %2" : "=v"(r) : "v"(lo), "v"(hi)); return r; }
;     __device__ __forceinline__ void operator()(f32x4 (&acc)[2][2][4][2], const Unit& u, int wr, int wc, int fr, int fq) const {
;     ...
; #pragma unroll
;                     for (int m = 0; m < 4; ++m) { const size_t off = (size_t)(row0 + ai * HALF + m * 16) * 1024 + col0 + bj * HALF + n * 16;
;                         f32x4 yo;
;                         if (Xin) yo = *(const f32x4*)(Xin + off);
;                         else { const u32x2 t = told[m]; yo = (f32x4){__uint_as_float(t.x << 16), __uint_as_float(t.x & 0xffff0000u), __uint_as_float(t.y << 16), __uint_as_float(t.y & 0xffff0000u)}; }
;                         const f32x4 yn = ((yo - mu[m]) * rs[m] * g4 + b4) * alpha + acc[ai][bj][m][n];
;                         acc[ai][bj][m][n] = yn;
;                         if (Yout) *(f32x4*)(Yout + off) = yn;
;                         else { u32x2 w; w.x = cvt_pk_bf16(yn[0], yn[1]); w.y = cvt_pk_bf16(yn[2], yn[3]); *(u32x2*)(YB + off) = w; } } } }
	v_lshlrev_b32_e32 v206, 16, v190
	v_and_b32_e32 v207, 0xffff0000, v190
	v_lshlrev_b32_e32 v190, 16, v191
	v_and_b32_e32 v191, 0xffff0000, v191
	v_sub_f32_e32 v206, v206, v178
	v_sub_f32_e32 v207, v207, v178
	v_sub_f32_e32 v190, v190, v178
	v_sub_f32_e32 v191, v191, v178
	v_pk_mul_f32 v[206:207], v[178:179], v[206:207] op_sel:[1,0]
	v_pk_mul_f32 v[190:191], v[178:179], v[190:191] op_sel:[1,0]
	v_pk_fma_f32 v[206:207], v[128:129], v[206:207], v[150:151]
	v_pk_fma_f32 v[190:191], v[130:131], v[190:191], v[152:153]
	v_pk_fma_f32 v[56:57], v[206:207], s[90:91], v[56:57] op_sel_hi:[1,0,1]
	v_pk_fma_f32 v[58:59], v[190:191], s[90:91], v[58:59] op_sel_hi:[1,0,1]
	global_store_dwordx4 v221, v[56:59], s[16:17] offset:0
	v_lshlrev_b32_e32 v208, 16, v192
	v_and_b32_e32 v209, 0xffff0000, v192
	v_lshlrev_b32_e32 v192, 16, v193
	v_and_b32_e32 v193, 0xffff0000, v193
	v_sub_f32_e32 v208, v208, v178
	v_sub_f32_e32 v209, v209, v178
	v_sub_f32_e32 v192, v192, v178
	v_sub_f32_e32 v193, v193, v178
	v_pk_mul_f32 v[208:209], v[178:179], v[208:209] op_sel:[1,0]
	v_pk_mul_f32 v[192:193], v[178:179], v[192:193] op_sel:[1,0]
	v_pk_fma_f32 v[208:209], v[132:133], v[208:209], v[154:155]
	v_pk_fma_f32 v[192:193], v[134:135], v[192:193], v[156:157]
	v_pk_fma_f32 v[84:85], v[208:209], s[90:91], v[84:85] op_sel_hi:[1,0,1]
	v_pk_fma_f32 v[86:87], v[192:193], s[90:91], v[86:87] op_sel_hi:[1,0,1]
	global_store_dwordx4 v221, v[84:87], s[16:17] offset:64
	v_lshlrev_b32_e32 v206, 16, v194
	v_and_b32_e32 v207, 0xffff0000, v194
	v_lshlrev_b32_e32 v194, 16, v195
	v_and_b32_e32 v195, 0xffff0000, v195
	v_sub_f32_e32 v206, v206, v178
	v_sub_f32_e32 v207, v207, v178
	v_sub_f32_e32 v194, v194, v178
	v_sub_f32_e32 v195, v195, v178
	v_pk_mul_f32 v[206:207], v[178:179], v[206:207] op_sel:[1,0]
	v_pk_mul_f32 v[194:195], v[178:179], v[194:195] op_sel:[1,0]
	v_pk_fma_f32 v[206:207], v[142:143], v[206:207], v[158:159]
	v_pk_fma_f32 v[194:195], v[144:145], v[194:195], v[160:161]
	v_pk_fma_f32 v[112:113], v[206:207], s[90:91], v[112:113] op_sel_hi:[1,0,1]
	v_pk_fma_f32 v[114:115], v[194:195], s[90:91], v[114:115] op_sel_hi:[1,0,1]
	global_store_dwordx4 v221, v[112:115], s[16:17] offset:512
	v_lshlrev_b32_e32 v208, 16, v196
	v_and_b32_e32 v209, 0xffff0000, v196
	v_lshlrev_b32_e32 v196, 16, v197
	v_and_b32_e32 v197, 0xffff0000, v197
	v_sub_f32_e32 v208, v208, v178
	v_sub_f32_e32 v209, v209, v178
	v_sub_f32_e32 v196, v196, v178
	v_sub_f32_e32 v197, v197, v178
	v_pk_mul_f32 v[208:209], v[178:179], v[208:209] op_sel:[1,0]
	v_pk_mul_f32 v[196:197], v[178:179], v[196:197] op_sel:[1,0]
	v_pk_fma_f32 v[208:209], v[146:147], v[208:209], v[174:175]
	v_pk_fma_f32 v[196:197], v[148:149], v[196:197], v[176:177]
	v_pk_fma_f32 v[116:117], v[208:209], s[90:91], v[116:117] op_sel_hi:[1,0,1]
	v_pk_fma_f32 v[118:119], v[196:197], s[90:91], v[118:119] op_sel_hi:[1,0,1]
	global_store_dwordx4 v221, v[116:119], s[16:17] offset:576
	s_add_u32 s16, s16, 0x10000
	s_addc_u32 s17, s17, 0
	global_load_dwordx2 v[178:179], v222, s[88:89] offset:1024
	global_load_dwordx2 v[190:191], v219, s[4:5] offset:0
	global_load_dwordx2 v[192:193], v219, s[4:5] offset:32
	global_load_dwordx2 v[194:195], v219, s[4:5] offset:256
	global_load_dwordx2 v[196:197], v219, s[4:5] offset:288
	s_add_u32 s4, s4, 0x8000
	s_addc_u32 s5, s5, 0
	s_waitcnt vmcnt(18)
	v_lshlrev_b32_e32 v206, 16, v198
	v_and_b32_e32 v207, 0xffff0000, v198
	v_lshlrev_b32_e32 v198, 16, v199
	v_and_b32_e32 v199, 0xffff0000, v199
	v_sub_f32_e32 v206, v206, v180
	v_sub_f32_e32 v207, v207, v180
	v_sub_f32_e32 v198, v198, v180
	v_sub_f32_e32 v199, v199, v180
	v_pk_mul_f32 v[206:207], v[180:181], v[206:207] op_sel:[1,0]
	v_pk_mul_f32 v[198:199], v[180:181], v[198:199] op_sel:[1,0]
	v_pk_fma_f32 v[206:207], v[128:129], v[206:207], v[150:151]
	v_pk_fma_f32 v[198:199], v[130:131], v[198:199], v[152:153]
	v_pk_fma_f32 v[48:49], v[206:207], s[90:91], v[48:49] op_sel_hi:[1,0,1]
	v_pk_fma_f32 v[50:51], v[198:199], s[90:91], v[50:51] op_sel_hi:[1,0,1]
	global_store_dwordx4 v221, v[48:51], s[16:17] offset:0
	v_lshlrev_b32_e32 v208, 16, v200
	v_and_b32_e32 v209, 0xffff0000, v200
	v_lshlrev_b32_e32 v200, 16, v201
	v_and_b32_e32 v201, 0xffff0000, v201
	v_sub_f32_e32 v208, v208, v180
	v_sub_f32_e32 v209, v209, v180
	v_sub_f32_e32 v200, v200, v180
	v_sub_f32_e32 v201, v201, v180
	v_pk_mul_f32 v[208:209], v[180:181], v[208:209] op_sel:[1,0]
	v_pk_mul_f32 v[200:201], v[180:181], v[200:201] op_sel:[1,0]
	v_pk_fma_f32 v[208:209], v[132:133], v[208:209], v[154:155]
	v_pk_fma_f32 v[200:201], v[134:135], v[200:201], v[156:157]
	v_pk_fma_f32 v[80:81], v[208:209], s[90:91], v[80:81] op_sel_hi:[1,0,1]
	v_pk_fma_f32 v[82:83], v[200:201], s[90:91], v[82:83] op_sel_hi:[1,0,1]
	global_store_dwordx4 v221, v[80:83], s[16:17] offset:64
	v_lshlrev_b32_e32 v206, 16, v202
	v_and_b32_e32 v207, 0xffff0000, v202
	v_lshlrev_b32_e32 v202, 16, v203
	v_and_b32_e32 v203, 0xffff0000, v203
	v_sub_f32_e32 v206, v206, v180
	v_sub_f32_e32 v207, v207, v180
	v_sub_f32_e32 v202, v202, v180
	v_sub_f32_e32 v203, v203, v180
	v_pk_mul_f32 v[206:207], v[180:181], v[206:207] op_sel:[1,0]
	v_pk_mul_f32 v[202:203], v[180:181], v[202:203] op_sel:[1,0]
	v_pk_fma_f32 v[206:207], v[142:143], v[206:207], v[158:159]
	v_pk_fma_f32 v[202:203], v[144:145], v[202:203], v[160:161]
	v_pk_fma_f32 v[108:109], v[206:207], s[90:91], v[108:109] op_sel_hi:[1,0,1]
	v_pk_fma_f32 v[110:111], v[202:203], s[90:91], v[110:111] op_sel_hi:[1,0,1]
	global_store_dwordx4 v221, v[108:111], s[16:17] offset:512
	v_lshlrev_b32_e32 v208, 16, v204
	v_and_b32_e32 v209, 0xffff0000, v204
	v_lshlrev_b32_e32 v204, 16, v205
	v_and_b32_e32 v205, 0xffff0000, v205
	v_sub_f32_e32 v208, v208, v180
	v_sub_f32_e32 v209, v209, v180
	v_sub_f32_e32 v204, v204, v180
	v_sub_f32_e32 v205, v205, v180
	v_pk_mul_f32 v[208:209], v[180:181], v[208:209] op_sel:[1,0]
	v_pk_mul_f32 v[204:205], v[180:181], v[204:205] op_sel:[1,0]
	v_pk_fma_f32 v[208:209], v[146:147], v[208:209], v[174:175]
	v_pk_fma_f32 v[204:205], v[148:149], v[204:205], v[176:177]
	v_pk_fma_f32 v[104:105], v[208:209], s[90:91], v[104:105] op_sel_hi:[1,0,1]
	v_pk_fma_f32 v[106:107], v[204:205], s[90:91], v[106:107] op_sel_hi:[1,0,1]
	global_store_dwordx4 v221, v[104:107], s[16:17] offset:576
	s_add_u32 s16, s16, 0x10000
	s_addc_u32 s17, s17, 0
	global_load_dwordx2 v[180:181], v222, s[88:89] offset:1152
	global_load_dwordx2 v[198:199], v219, s[4:5] offset:0
	global_load_dwordx2 v[200:201], v219, s[4:5] offset:32
	global_load_dwordx2 v[202:203], v219, s[4:5] offset:256
	global_load_dwordx2 v[204:205], v219, s[4:5] offset:288
	s_add_u32 s4, s4, 0x8000
	s_addc_u32 s5, s5, 0
	s_waitcnt vmcnt(18)
; __device__ __forceinline__ unsigned cvt_pk_bf16(float lo, float hi) { unsigned r; asm volatile("v_cvt_pk_bf16_f32 %0, %1, %2" : "=v"(r) : "v"(lo), "v"(hi)); return r; }
;     __device__ __forceinline__ void operator()(f32x4 (&acc)[2][2][4][2], const Unit& u, int wr, int wc, int fr, int fq) const {
;     ...
; #pragma unroll
;                     for (int m = 0; m < 4; ++m) { const size_t off = (size_t)(row0 + ai * HALF + m * 16) * 1024 + col0 + bj * HALF + n * 16;
;                         f32x4 yo;
;                         if (Xin) yo = *(const f32x4*)(Xin + off);
;                         else { const u32x2 t = told[m]; yo = (f32x4){__uint_as_float(t.x << 16), __uint_as_float(t.x & 0xffff0000u), __uint_as_float(t.y << 16), __uint_as_float(t.y & 0xffff0000u)}; }
;                         const f32x4 yn = ((yo - mu[m]) * rs[m] * g4 + b4) * alpha + acc[ai][bj][m][n];
;                         acc[ai][bj][m][n] = yn;
;                         if (Yout) *(f32x4*)(Yout + off) = yn;
;                         else { u32x2 w; w.x = cvt_pk_bf16(yn[0], yn[1]); w.y = cvt_pk_bf16(yn[2], yn[3]); *(u32x2*)(YB + off) = w; } } } }
	v_lshlrev_b32_e32 v206, 16, v182
	v_and_b32_e32 v207, 0xffff0000, v182
	v_lshlrev_b32_e32 v182, 16, v183
	v_and_b32_e32 v183, 0xffff0000, v183
	v_sub_f32_e32 v206, v206, v162
	v_sub_f32_e32 v207, v207, v162
	v_sub_f32_e32 v182, v182, v162
	v_sub_f32_e32 v183, v183, v162
	v_pk_mul_f32 v[206:207], v[162:163], v[206:207] op_sel:[1,0]
	v_pk_mul_f32 v[182:183], v[162:163], v[182:183] op_sel:[1,0]
	v_pk_fma_f32 v[206:207], v[128:129], v[206:207], v[150:151]
	v_pk_fma_f32 v[182:183], v[130:131], v[182:183], v[152:153]
	v_pk_fma_f32 v[40:41], v[206:207], s[90:91], v[40:41] op_sel_hi:[1,0,1]
	v_pk_fma_f32 v[42:43], v[182:183], s[90:91], v[42:43] op_sel_hi:[1,0,1]
	global_store_dwordx4 v221, v[40:43], s[16:17] offset:0
	v_lshlrev_b32_e32 v208, 16, v184
	v_and_b32_e32 v209, 0xffff0000, v184
	v_lshlrev_b32_e32 v184, 16, v185
	v_and_b32_e32 v185, 0xffff0000, v185
	v_sub_f32_e32 v208, v208, v162
	v_sub_f32_e32 v209, v209, v162
	v_sub_f32_e32 v184, v184, v162
	v_sub_f32_e32 v185, v185, v162
	v_pk_mul_f32 v[208:209], v[162:163], v[208:209] op_sel:[1,0]
	v_pk_mul_f32 v[184:185], v[162:163], v[184:185] op_sel:[1,0]
	v_pk_fma_f32 v[208:209], v[132:133], v[208:209], v[154:155]
	v_pk_fma_f32 v[184:185], v[134:135], v[184:185], v[156:157]
	v_pk_fma_f32 v[72:73], v[208:209], s[90:91], v[72:73] op_sel_hi:[1,0,1]
	v_pk_fma_f32 v[74:75], v[184:185], s[90:91], v[74:75] op_sel_hi:[1,0,1]
	global_store_dwordx4 v221, v[72:75], s[16:17] offset:64
	v_lshlrev_b32_e32 v206, 16, v186
	v_and_b32_e32 v207, 0xffff0000, v186
	v_lshlrev_b32_e32 v186, 16, v187
	v_and_b32_e32 v187, 0xffff0000, v187
	v_sub_f32_e32 v206, v206, v162
	v_sub_f32_e32 v207, v207, v162
	v_sub_f32_e32 v186, v186, v162
	v_sub_f32_e32 v187, v187, v162
	v_pk_mul_f32 v[206:207], v[162:163], v[206:207] op_sel:[1,0]
	v_pk_mul_f32 v[186:187], v[162:163], v[186:187] op_sel:[1,0]
	v_pk_fma_f32 v[206:207], v[142:143], v[206:207], v[158:159]
	v_pk_fma_f32 v[186:187], v[144:145], v[186:187], v[160:161]
	v_pk_fma_f32 v[100:101], v[206:207], s[90:91], v[100:101] op_sel_hi:[1,0,1]
	v_pk_fma_f32 v[102:103], v[186:187], s[90:91], v[102:103] op_sel_hi:[1,0,1]
	global_store_dwordx4 v221, v[100:103], s[16:17] offset:512
	v_lshlrev_b32_e32 v208, 16, v188
	v_and_b32_e32 v209, 0xffff0000, v188
	v_lshlrev_b32_e32 v188, 16, v189
	v_and_b32_e32 v189, 0xffff0000, v189
	v_sub_f32_e32 v208, v208, v162
	v_sub_f32_e32 v209, v209, v162
	v_sub_f32_e32 v188, v188, v162
	v_sub_f32_e32 v189, v189, v162
	v_pk_mul_f32 v[208:209], v[162:163], v[208:209] op_sel:[1,0]
	v_pk_mul_f32 v[188:189], v[162:163], v[188:189] op_sel:[1,0]
	v_pk_fma_f32 v[208:209], v[146:147], v[208:209], v[174:175]
	v_pk_fma_f32 v[188:189], v[148:149], v[188:189], v[176:177]
	v_pk_fma_f32 v[96:97], v[208:209], s[90:91], v[96:97] op_sel_hi:[1,0,1]
	v_pk_fma_f32 v[98:99], v[188:189], s[90:91], v[98:99] op_sel_hi:[1,0,1]
	global_store_dwordx4 v221, v[96:99], s[16:17] offset:576
	s_add_u32 s16, s16, 0x50000
	s_addc_u32 s17, s17, 0
	global_load_dwordx2 v[162:163], v222, s[88:89] offset:1280
	global_load_dwordx2 v[182:183], v219, s[4:5] offset:0
	global_load_dwordx2 v[184:185], v219, s[4:5] offset:32
	global_load_dwordx2 v[186:187], v219, s[4:5] offset:256
	global_load_dwordx2 v[188:189], v219, s[4:5] offset:288
	s_add_u32 s4, s4, 0x8000
	s_addc_u32 s5, s5, 0
	s_waitcnt vmcnt(18)
	v_lshlrev_b32_e32 v206, 16, v190
	v_and_b32_e32 v207, 0xffff0000, v190
	v_lshlrev_b32_e32 v190, 16, v191
	v_and_b32_e32 v191, 0xffff0000, v191
	v_sub_f32_e32 v206, v206, v178
	v_sub_f32_e32 v207, v207, v178
	v_sub_f32_e32 v190, v190, v178
	v_sub_f32_e32 v191, v191, v178
	v_pk_mul_f32 v[206:207], v[178:179], v[206:207] op_sel:[1,0]
	v_pk_mul_f32 v[190:191], v[178:179], v[190:191] op_sel:[1,0]
	v_pk_fma_f32 v[206:207], v[128:129], v[206:207], v[150:151]
	v_pk_fma_f32 v[190:191], v[130:131], v[190:191], v[152:153]
	v_pk_fma_f32 v[88:89], v[206:207], s[90:91], v[88:89] op_sel_hi:[1,0,1]
	v_pk_fma_f32 v[90:91], v[190:191], s[90:91], v[90:91] op_sel_hi:[1,0,1]
	global_store_dwordx4 v221, v[88:91], s[16:17] offset:0
	v_lshlrev_b32_e32 v208, 16, v192
	v_and_b32_e32 v209, 0xffff0000, v192
	v_lshlrev_b32_e32 v192, 16, v193
	v_and_b32_e32 v193, 0xffff0000, v193
	v_sub_f32_e32 v208, v208, v178
	v_sub_f32_e32 v209, v209, v178
	v_sub_f32_e32 v192, v192, v178
	v_sub_f32_e32 v193, v193, v178
	v_pk_mul_f32 v[208:209], v[178:179], v[208:209] op_sel:[1,0]
	v_pk_mul_f32 v[192:193], v[178:179], v[192:193] op_sel:[1,0]
	v_pk_fma_f32 v[208:209], v[132:133], v[208:209], v[154:155]
	v_pk_fma_f32 v[192:193], v[134:135], v[192:193], v[156:157]
	v_pk_fma_f32 v[52:53], v[208:209], s[90:91], v[52:53] op_sel_hi:[1,0,1]
	v_pk_fma_f32 v[54:55], v[192:193], s[90:91], v[54:55] op_sel_hi:[1,0,1]
	global_store_dwordx4 v221, v[52:55], s[16:17] offset:64
	v_lshlrev_b32_e32 v206, 16, v194
	v_and_b32_e32 v207, 0xffff0000, v194
	v_lshlrev_b32_e32 v194, 16, v195
	v_and_b32_e32 v195, 0xffff0000, v195
	v_sub_f32_e32 v206, v206, v178
	v_sub_f32_e32 v207, v207, v178
	v_sub_f32_e32 v194, v194, v178
	v_sub_f32_e32 v195, v195, v178
	v_pk_mul_f32 v[206:207], v[178:179], v[206:207] op_sel:[1,0]
	v_pk_mul_f32 v[194:195], v[178:179], v[194:195] op_sel:[1,0]
	v_pk_fma_f32 v[206:207], v[142:143], v[206:207], v[158:159]
	v_pk_fma_f32 v[194:195], v[144:145], v[194:195], v[160:161]
	v_pk_fma_f32 v[28:29], v[206:207], s[90:91], v[28:29] op_sel_hi:[1,0,1]
	v_pk_fma_f32 v[30:31], v[194:195], s[90:91], v[30:31] op_sel_hi:[1,0,1]
	global_store_dwordx4 v221, v[28:31], s[16:17] offset:512
	v_lshlrev_b32_e32 v208, 16, v196
	v_and_b32_e32 v209, 0xffff0000, v196
	v_lshlrev_b32_e32 v196, 16, v197
	v_and_b32_e32 v197, 0xffff0000, v197
	v_sub_f32_e32 v208, v208, v178
	v_sub_f32_e32 v209, v209, v178
	v_sub_f32_e32 v196, v196, v178
	v_sub_f32_e32 v197, v197, v178
	v_pk_mul_f32 v[208:209], v[178:179], v[208:209] op_sel:[1,0]
	v_pk_mul_f32 v[196:197], v[178:179], v[196:197] op_sel:[1,0]
	v_pk_fma_f32 v[208:209], v[146:147], v[208:209], v[174:175]
	v_pk_fma_f32 v[196:197], v[148:149], v[196:197], v[176:177]
	v_pk_fma_f32 v[12:13], v[208:209], s[90:91], v[12:13] op_sel_hi:[1,0,1]
	v_pk_fma_f32 v[14:15], v[196:197], s[90:91], v[14:15] op_sel_hi:[1,0,1]
	global_store_dwordx4 v221, v[12:15], s[16:17] offset:576
	s_add_u32 s16, s16, 0x10000
	s_addc_u32 s17, s17, 0
	global_load_dwordx2 v[178:179], v222, s[88:89] offset:1408
	global_load_dwordx2 v[190:191], v219, s[4:5] offset:0
	global_load_dwordx2 v[192:193], v219, s[4:5] offset:32
	global_load_dwordx2 v[194:195], v219, s[4:5] offset:256
	global_load_dwordx2 v[196:197], v219, s[4:5] offset:288
	s_waitcnt vmcnt(18)
; __device__ __forceinline__ unsigned cvt_pk_bf16(float lo, float hi) { unsigned r; asm volatile("v_cvt_pk_bf16_f32 %0, %1, %2" : "=v"(r) : "v"(lo), "v"(hi)); return r; }
;     __device__ __forceinline__ void operator()(f32x4 (&acc)[2][2][4][2], const Unit& u, int wr, int wc, int fr, int fq) const {
;     ...
;                     for (int m = 0; m < 4; ++m) { const size_t off = (size_t)(row0 + ai * HALF + m * 16) * 1024 + col0 + bj * HALF + n * 16;
;                         f32x4 yo;
;                         if (Xin) yo = *(const f32x4*)(Xin + off);
;                         else { const u32x2 t = told[m]; yo = (f32x4){__uint_as_float(t.x << 16), __uint_as_float(t.x & 0xffff0000u), __uint_as_float(t.y << 16), __uint_as_float(t.y & 0xffff0000u)}; }
;                         const f32x4 yn = ((yo - mu[m]) * rs[m] * g4 + b4) * alpha + acc[ai][bj][m][n];
;                         acc[ai][bj][m][n] = yn;
;                         if (Yout) *(f32x4*)(Yout + off) = yn;
;                         else { u32x2 w; w.x = cvt_pk_bf16(yn[0], yn[1]); w.y = cvt_pk_bf16(yn[2], yn[3]); *(u32x2*)(YB + off) = w; } } } }
	v_lshlrev_b32_e32 v206, 16, v198
	v_and_b32_e32 v207, 0xffff0000, v198
	v_lshlrev_b32_e32 v198, 16, v199
	v_and_b32_e32 v199, 0xffff0000, v199
	v_sub_f32_e32 v206, v206, v180
	v_sub_f32_e32 v207, v207, v180
	v_sub_f32_e32 v198, v198, v180
	v_sub_f32_e32 v199, v199, v180
	v_pk_mul_f32 v[206:207], v[180:181], v[206:207] op_sel:[1,0]
	v_pk_mul_f32 v[198:199], v[180:181], v[198:199] op_sel:[1,0]
	v_pk_fma_f32 v[206:207], v[128:129], v[206:207], v[150:151]
	v_pk_fma_f32 v[198:199], v[130:131], v[198:199], v[152:153]
	v_pk_fma_f32 v[76:77], v[206:207], s[90:91], v[76:77] op_sel_hi:[1,0,1]
	v_pk_fma_f32 v[78:79], v[198:199], s[90:91], v[78:79] op_sel_hi:[1,0,1]
	global_store_dwordx4 v221, v[76:79], s[16:17] offset:0
	v_lshlrev_b32_e32 v208, 16, v200
	v_and_b32_e32 v209, 0xffff0000, v200
	v_lshlrev_b32_e32 v200, 16, v201
	v_and_b32_e32 v201, 0xffff0000, v201
	v_sub_f32_e32 v208, v208, v180
	v_sub_f32_e32 v209, v209, v180
	v_sub_f32_e32 v200, v200, v180
	v_sub_f32_e32 v201, v201, v180
	v_pk_mul_f32 v[208:209], v[180:181], v[208:209] op_sel:[1,0]
	v_pk_mul_f32 v[200:201], v[180:181], v[200:201] op_sel:[1,0]
	v_pk_fma_f32 v[208:209], v[132:133], v[208:209], v[154:155]
	v_pk_fma_f32 v[200:201], v[134:135], v[200:201], v[156:157]
	v_pk_fma_f32 v[44:45], v[208:209], s[90:91], v[44:45] op_sel_hi:[1,0,1]
	v_pk_fma_f32 v[46:47], v[200:201], s[90:91], v[46:47] op_sel_hi:[1,0,1]
	global_store_dwordx4 v221, v[44:47], s[16:17] offset:64
	v_lshlrev_b32_e32 v206, 16, v202
	v_and_b32_e32 v207, 0xffff0000, v202
	v_lshlrev_b32_e32 v202, 16, v203
	v_and_b32_e32 v203, 0xffff0000, v203
	v_sub_f32_e32 v206, v206, v180
	v_sub_f32_e32 v207, v207, v180
	v_sub_f32_e32 v202, v202, v180
	v_sub_f32_e32 v203, v203, v180
	v_pk_mul_f32 v[206:207], v[180:181], v[206:207] op_sel:[1,0]
	v_pk_mul_f32 v[202:203], v[180:181], v[202:203] op_sel:[1,0]
	v_pk_fma_f32 v[206:207], v[142:143], v[206:207], v[158:159]
	v_pk_fma_f32 v[202:203], v[144:145], v[202:203], v[160:161]
	v_pk_fma_f32 v[24:25], v[206:207], s[90:91], v[24:25] op_sel_hi:[1,0,1]
	v_pk_fma_f32 v[26:27], v[202:203], s[90:91], v[26:27] op_sel_hi:[1,0,1]
	global_store_dwordx4 v221, v[24:27], s[16:17] offset:512
	v_lshlrev_b32_e32 v208, 16, v204
	v_and_b32_e32 v209, 0xffff0000, v204
	v_lshlrev_b32_e32 v204, 16, v205
	v_and_b32_e32 v205, 0xffff0000, v205
	v_sub_f32_e32 v208, v208, v180
	v_sub_f32_e32 v209, v209, v180
	v_sub_f32_e32 v204, v204, v180
	v_sub_f32_e32 v205, v205, v180
	v_pk_mul_f32 v[208:209], v[180:181], v[208:209] op_sel:[1,0]
	v_pk_mul_f32 v[204:205], v[180:181], v[204:205] op_sel:[1,0]
	v_pk_fma_f32 v[208:209], v[146:147], v[208:209], v[174:175]
	v_pk_fma_f32 v[204:205], v[148:149], v[204:205], v[176:177]
	v_pk_fma_f32 v[8:9], v[208:209], s[90:91], v[8:9] op_sel_hi:[1,0,1]
	v_pk_fma_f32 v[10:11], v[204:205], s[90:91], v[10:11] op_sel_hi:[1,0,1]
	global_store_dwordx4 v221, v[8:11], s[16:17] offset:576
	s_add_u32 s16, s16, 0x10000
	s_addc_u32 s17, s17, 0
	s_waitcnt vmcnt(13)
	v_lshlrev_b32_e32 v206, 16, v182
	v_and_b32_e32 v207, 0xffff0000, v182
	v_lshlrev_b32_e32 v182, 16, v183
	v_and_b32_e32 v183, 0xffff0000, v183
	v_sub_f32_e32 v206, v206, v162
	v_sub_f32_e32 v207, v207, v162
	v_sub_f32_e32 v182, v182, v162
	v_sub_f32_e32 v183, v183, v162
	v_pk_mul_f32 v[206:207], v[162:163], v[206:207] op_sel:[1,0]
	v_pk_mul_f32 v[182:183], v[162:163], v[182:183] op_sel:[1,0]
	v_pk_fma_f32 v[206:207], v[128:129], v[206:207], v[150:151]
	v_pk_fma_f32 v[182:183], v[130:131], v[182:183], v[152:153]
	v_pk_fma_f32 v[68:69], v[206:207], s[90:91], v[68:69] op_sel_hi:[1,0,1]
	v_pk_fma_f32 v[70:71], v[182:183], s[90:91], v[70:71] op_sel_hi:[1,0,1]
	global_store_dwordx4 v221, v[68:71], s[16:17] offset:0
	v_lshlrev_b32_e32 v208, 16, v184
	v_and_b32_e32 v209, 0xffff0000, v184
	v_lshlrev_b32_e32 v184, 16, v185
	v_and_b32_e32 v185, 0xffff0000, v185
	v_sub_f32_e32 v208, v208, v162
	v_sub_f32_e32 v209, v209, v162
	v_sub_f32_e32 v184, v184, v162
	v_sub_f32_e32 v185, v185, v162
	v_pk_mul_f32 v[208:209], v[162:163], v[208:209] op_sel:[1,0]
	v_pk_mul_f32 v[184:185], v[162:163], v[184:185] op_sel:[1,0]
	v_pk_fma_f32 v[208:209], v[132:133], v[208:209], v[154:155]
	v_pk_fma_f32 v[184:185], v[134:135], v[184:185], v[156:157]
	v_pk_fma_f32 v[36:37], v[208:209], s[90:91], v[36:37] op_sel_hi:[1,0,1]
	v_pk_fma_f32 v[38:39], v[184:185], s[90:91], v[38:39] op_sel_hi:[1,0,1]
	global_store_dwordx4 v221, v[36:39], s[16:17] offset:64
	v_lshlrev_b32_e32 v206, 16, v186
	v_and_b32_e32 v207, 0xffff0000, v186
	v_lshlrev_b32_e32 v186, 16, v187
	v_and_b32_e32 v187, 0xffff0000, v187
	v_sub_f32_e32 v206, v206, v162
	v_sub_f32_e32 v207, v207, v162
	v_sub_f32_e32 v186, v186, v162
	v_sub_f32_e32 v187, v187, v162
	v_pk_mul_f32 v[206:207], v[162:163], v[206:207] op_sel:[1,0]
	v_pk_mul_f32 v[186:187], v[162:163], v[186:187] op_sel:[1,0]
	v_pk_fma_f32 v[206:207], v[142:143], v[206:207], v[158:159]
	v_pk_fma_f32 v[186:187], v[144:145], v[186:187], v[160:161]
	v_pk_fma_f32 v[20:21], v[206:207], s[90:91], v[20:21] op_sel_hi:[1,0,1]
	v_pk_fma_f32 v[22:23], v[186:187], s[90:91], v[22:23] op_sel_hi:[1,0,1]
	global_store_dwordx4 v221, v[20:23], s[16:17] offset:512
	v_lshlrev_b32_e32 v208, 16, v188
	v_and_b32_e32 v209, 0xffff0000, v188
	v_lshlrev_b32_e32 v188, 16, v189
	v_and_b32_e32 v189, 0xffff0000, v189
	v_sub_f32_e32 v208, v208, v162
	v_sub_f32_e32 v209, v209, v162
	v_sub_f32_e32 v188, v188, v162
	v_sub_f32_e32 v189, v189, v162
	v_pk_mul_f32 v[208:209], v[162:163], v[208:209] op_sel:[1,0]
	v_pk_mul_f32 v[188:189], v[162:163], v[188:189] op_sel:[1,0]
	v_pk_fma_f32 v[208:209], v[146:147], v[208:209], v[174:175]
	v_pk_fma_f32 v[188:189], v[148:149], v[188:189], v[176:177]
	v_pk_fma_f32 v[4:5], v[208:209], s[90:91], v[4:5] op_sel_hi:[1,0,1]
	v_pk_fma_f32 v[6:7], v[188:189], s[90:91], v[6:7] op_sel_hi:[1,0,1]
	global_store_dwordx4 v221, v[4:7], s[16:17] offset:576
	s_add_u32 s16, s16, 0x10000
	s_addc_u32 s17, s17, 0
	s_waitcnt vmcnt(8)
; #define PG8_LAS __attribute__((address_space(3)))
; __device__ __forceinline__ unsigned cvt_pk_bf16(float lo, float hi) { unsigned r; asm volatile("v_cvt_pk_bf16_f32 %0, %1, %2" : "=v"(r) : "v"(lo), "v"(hi)); return r; }
;     __device__ __forceinline__ void operator()(f32x4 (&acc)[2][2][4][2], const Unit& u, int wr, int wc, int fr, int fq) const {
;     ...
;                     for (int m = 0; m < 4; ++m) { const size_t off = (size_t)(row0 + ai * HALF + m * 16) * 1024 + col0 + bj * HALF + n * 16;
;                         f32x4 yo;
;                         if (Xin) yo = *(const f32x4*)(Xin + off);
;                         else { const u32x2 t = told[m]; yo = (f32x4){__uint_as_float(t.x << 16), __uint_as_float(t.x & 0xffff0000u), __uint_as_float(t.y << 16), __uint_as_float(t.y & 0xffff0000u)}; }
;                         const f32x4 yn = ((yo - mu[m]) * rs[m] * g4 + b4) * alpha + acc[ai][bj][m][n];
;                         acc[ai][bj][m][n] = yn;
;                         if (Yout) *(f32x4*)(Yout + off) = yn;
;                         else { u32x2 w; w.x = cvt_pk_bf16(yn[0], yn[1]); w.y = cvt_pk_bf16(yn[2], yn[3]); *(u32x2*)(YB + off) = w; } } } }
;         PG8_LAS f32x2* P = (PG8_LAS f32x2*)(lds + 131072);
; #pragma unroll
;         for (int ai = 0; ai < 2; ++ai)
; #pragma unroll
;             for (int m = 0; m < 4; ++m) {
;                 float s = 0.f;
; #pragma unroll
;                 for (int bj = 0; bj < 2; ++bj)
; #pragma unroll
;                     for (int n = 0; n < 2; ++n) { const f32x4 x = acc[ai][bj][m][n]; s += (x[0] + x[1]) + (x[2] + x[3]); }
;                 s += __shfl_xor(s, 16); s += __shfl_xor(s, 32);
	v_lshlrev_b32_e32 v206, 16, v190
	v_and_b32_e32 v207, 0xffff0000, v190
	v_lshlrev_b32_e32 v190, 16, v191
	v_and_b32_e32 v191, 0xffff0000, v191
	v_sub_f32_e32 v206, v206, v178
	v_sub_f32_e32 v207, v207, v178
	v_sub_f32_e32 v190, v190, v178
	v_sub_f32_e32 v191, v191, v178
	v_pk_mul_f32 v[206:207], v[178:179], v[206:207] op_sel:[1,0]
	v_pk_mul_f32 v[190:191], v[178:179], v[190:191] op_sel:[1,0]
	v_pk_fma_f32 v[206:207], v[128:129], v[206:207], v[150:151]
	v_pk_fma_f32 v[190:191], v[130:131], v[190:191], v[152:153]
	v_pk_fma_f32 v[64:65], v[206:207], s[90:91], v[64:65] op_sel_hi:[1,0,1]
	v_pk_fma_f32 v[66:67], v[190:191], s[90:91], v[66:67] op_sel_hi:[1,0,1]
	global_store_dwordx4 v221, v[64:67], s[16:17] offset:0
	v_lshlrev_b32_e32 v208, 16, v192
	v_and_b32_e32 v209, 0xffff0000, v192
	v_lshlrev_b32_e32 v192, 16, v193
	v_and_b32_e32 v193, 0xffff0000, v193
	v_sub_f32_e32 v208, v208, v178
	v_sub_f32_e32 v209, v209, v178
	v_sub_f32_e32 v192, v192, v178
	v_sub_f32_e32 v193, v193, v178
	v_pk_mul_f32 v[208:209], v[178:179], v[208:209] op_sel:[1,0]
	v_pk_mul_f32 v[192:193], v[178:179], v[192:193] op_sel:[1,0]
	v_pk_fma_f32 v[208:209], v[132:133], v[208:209], v[154:155]
	v_pk_fma_f32 v[192:193], v[134:135], v[192:193], v[156:157]
	v_pk_fma_f32 v[32:33], v[208:209], s[90:91], v[32:33] op_sel_hi:[1,0,1]
	v_pk_fma_f32 v[34:35], v[192:193], s[90:91], v[34:35] op_sel_hi:[1,0,1]
	global_store_dwordx4 v221, v[32:35], s[16:17] offset:64
	v_lshlrev_b32_e32 v206, 16, v194
	v_and_b32_e32 v207, 0xffff0000, v194
	v_lshlrev_b32_e32 v194, 16, v195
	v_and_b32_e32 v195, 0xffff0000, v195
	v_sub_f32_e32 v206, v206, v178
	v_sub_f32_e32 v207, v207, v178
	v_sub_f32_e32 v194, v194, v178
	v_sub_f32_e32 v195, v195, v178
	v_pk_mul_f32 v[206:207], v[178:179], v[206:207] op_sel:[1,0]
	v_pk_mul_f32 v[194:195], v[178:179], v[194:195] op_sel:[1,0]
	v_pk_fma_f32 v[206:207], v[142:143], v[206:207], v[158:159]
	v_pk_fma_f32 v[194:195], v[144:145], v[194:195], v[160:161]
	v_pk_fma_f32 v[16:17], v[206:207], s[90:91], v[16:17] op_sel_hi:[1,0,1]
	v_pk_fma_f32 v[18:19], v[194:195], s[90:91], v[18:19] op_sel_hi:[1,0,1]
	global_store_dwordx4 v221, v[16:19], s[16:17] offset:512
	v_lshlrev_b32_e32 v208, 16, v196
	v_and_b32_e32 v209, 0xffff0000, v196
	v_lshlrev_b32_e32 v196, 16, v197
	v_and_b32_e32 v197, 0xffff0000, v197
	v_sub_f32_e32 v208, v208, v178
	v_sub_f32_e32 v209, v209, v178
	v_sub_f32_e32 v196, v196, v178
	v_sub_f32_e32 v197, v197, v178
	v_pk_mul_f32 v[208:209], v[178:179], v[208:209] op_sel:[1,0]
	v_pk_mul_f32 v[196:197], v[178:179], v[196:197] op_sel:[1,0]
	v_pk_fma_f32 v[208:209], v[146:147], v[208:209], v[174:175]
	v_pk_fma_f32 v[196:197], v[148:149], v[196:197], v[176:177]
	v_pk_fma_f32 v[0:1], v[208:209], s[90:91], v[0:1] op_sel_hi:[1,0,1]
	v_pk_fma_f32 v[2:3], v[196:197], s[90:91], v[2:3] op_sel_hi:[1,0,1]
	global_store_dwordx4 v221, v[0:3], s[16:17] offset:576
	v_xor_b32_e32 v198, 16, v230
	v_xor_b32_e32 v197, 32, v230
	v_lshlrev_b32_e32 v198, 2, v198
	v_lshlrev_b32_e32 v197, 2, v197
	v_add_f32_e32 v200, v60, v61
	v_add_f32_e32 v199, v62, v63
	v_add_f32_e32 v219, v200, v199
	v_add_f32_e32 v200, v92, v93
	v_add_f32_e32 v199, v94, v95
	v_add_f32_e32 v200, v200, v199
	v_add_f32_e32 v219, v219, v200
	v_add_f32_e32 v200, v120, v121
	v_add_f32_e32 v199, v122, v123
	v_add_f32_e32 v200, v200, v199
	v_add_f32_e32 v219, v219, v200
	v_add_f32_e32 v200, v124, v125
	v_add_f32_e32 v199, v126, v127
	v_add_f32_e32 v200, v200, v199
	v_add_f32_e32 v219, v219, v200
	v_add_f32_e32 v200, v56, v57
	v_add_f32_e32 v199, v58, v59
	v_add_f32_e32 v223, v200, v199
	v_add_f32_e32 v200, v84, v85
	v_add_f32_e32 v199, v86, v87
	v_add_f32_e32 v200, v200, v199
	v_add_f32_e32 v223, v223, v200
	v_add_f32_e32 v200, v112, v113
	v_add_f32_e32 v199, v114, v115
	v_add_f32_e32 v200, v200, v199
	v_add_f32_e32 v223, v223, v200
	v_add_f32_e32 v200, v116, v117
	v_add_f32_e32 v199, v118, v119
	v_add_f32_e32 v200, v200, v199
	v_add_f32_e32 v223, v223, v200
	v_add_f32_e32 v200, v48, v49
	v_add_f32_e32 v199, v50, v51
	v_add_f32_e32 v222, v200, v199
	v_add_f32_e32 v200, v80, v81
	v_add_f32_e32 v199, v82, v83
	v_add_f32_e32 v200, v200, v199
	v_add_f32_e32 v222, v222, v200
	v_add_f32_e32 v200, v108, v109
	v_add_f32_e32 v199, v110, v111
	v_add_f32_e32 v200, v200, v199
	v_add_f32_e32 v222, v222, v200
	v_add_f32_e32 v200, v104, v105
	v_add_f32_e32 v199, v106, v107
	v_add_f32_e32 v200, v200, v199
	v_add_f32_e32 v222, v222, v200
	v_add_f32_e32 v200, v40, v41
	v_add_f32_e32 v199, v42, v43
	v_add_f32_e32 v221, v200, v199
	v_add_f32_e32 v200, v72, v73
	v_add_f32_e32 v199, v74, v75
	v_add_f32_e32 v200, v200, v199
	v_add_f32_e32 v221, v221, v200
	v_add_f32_e32 v200, v100, v101
	v_add_f32_e32 v199, v102, v103
	v_add_f32_e32 v200, v200, v199
	v_add_f32_e32 v221, v221, v200
	v_add_f32_e32 v200, v96, v97
	v_add_f32_e32 v199, v98, v99
	v_add_f32_e32 v200, v200, v199
	v_add_f32_e32 v221, v221, v200
	v_add_f32_e32 v200, v88, v89
	v_add_f32_e32 v199, v90, v91
	v_add_f32_e32 v220, v200, v199
	v_add_f32_e32 v200, v52, v53
	v_add_f32_e32 v199, v54, v55
	v_add_f32_e32 v200, v200, v199
	v_add_f32_e32 v220, v220, v200
	v_add_f32_e32 v200, v28, v29
	v_add_f32_e32 v199, v30, v31
	v_add_f32_e32 v200, v200, v199
	v_add_f32_e32 v220, v220, v200
	v_add_f32_e32 v200, v12, v13
	v_add_f32_e32 v199, v14, v15
	v_add_f32_e32 v200, v200, v199
	v_add_f32_e32 v220, v220, v200
	v_add_f32_e32 v200, v76, v77
	v_add_f32_e32 v199, v78, v79
	v_add_f32_e32 v211, v200, v199
	v_add_f32_e32 v200, v44, v45
	v_add_f32_e32 v199, v46, v47
	v_add_f32_e32 v200, v200, v199
	v_add_f32_e32 v211, v211, v200
	v_add_f32_e32 v200, v24, v25
	v_add_f32_e32 v199, v26, v27
	v_add_f32_e32 v200, v200, v199
	v_add_f32_e32 v211, v211, v200
	v_add_f32_e32 v200, v8, v9
	v_add_f32_e32 v199, v10, v11
	v_add_f32_e32 v200, v200, v199
	v_add_f32_e32 v211, v211, v200
	v_add_f32_e32 v200, v68, v69
	v_add_f32_e32 v199, v70, v71
	v_add_f32_e32 v210, v200, v199
	v_add_f32_e32 v200, v36, v37
	v_add_f32_e32 v199, v38, v39
	v_add_f32_e32 v200, v200, v199
	v_add_f32_e32 v210, v210, v200
	v_add_f32_e32 v200, v20, v21
	v_add_f32_e32 v199, v22, v23
	v_add_f32_e32 v200, v200, v199
	v_add_f32_e32 v210, v210, v200
	v_add_f32_e32 v200, v4, v5
	v_add_f32_e32 v199, v6, v7
	v_add_f32_e32 v200, v200, v199
	v_add_f32_e32 v210, v210, v200
	v_add_f32_e32 v200, v64, v65
	v_add_f32_e32 v199, v66, v67
	v_add_f32_e32 v209, v200, v199
	v_add_f32_e32 v200, v32, v33
	v_add_f32_e32 v199, v34, v35
	v_add_f32_e32 v200, v200, v199
	v_add_f32_e32 v209, v209, v200
	v_add_f32_e32 v200, v16, v17
	v_add_f32_e32 v199, v18, v19
	v_add_f32_e32 v200, v200, v199
	v_add_f32_e32 v209, v209, v200
	v_add_f32_e32 v200, v0, v1
	v_add_f32_e32 v199, v2, v3
	v_add_f32_e32 v200, v200, v199
	v_add_f32_e32 v209, v209, v200
	ds_bpermute_b32 v208, v198, v219
	ds_bpermute_b32 v207, v198, v223
	ds_bpermute_b32 v206, v198, v222
	ds_bpermute_b32 v205, v198, v221
	ds_bpermute_b32 v204, v198, v220
	ds_bpermute_b32 v203, v198, v211
	ds_bpermute_b32 v202, v198, v210
	ds_bpermute_b32 v201, v198, v209
	s_waitcnt lgkmcnt(0)
;     __device__ __forceinline__ void operator()(f32x4 (&acc)[2][2][4][2], const Unit& u, int wr, int wc, int fr, int fq) const {
;     ...
;                 s += __shfl_xor(s, 16); s += __shfl_xor(s, 32);
;                 const float mw = s * (1.0f / 64.0f); float q = 0.f;
; #pragma unroll
;                 for (int bj = 0; bj < 2; ++bj)
; #pragma unroll
;                     for (int n = 0; n < 2; ++n) { const f32x4 d = acc[ai][bj][m][n] - mw; q += (d[0] * d[0] + d[1] * d[1]) + (d[2] * d[2] + d[3] * d[3]); }
;                 q += __shfl_xor(q, 16); q += __shfl_xor(q, 32);
	v_add_f32_e32 v219, v219, v208
	v_add_f32_e32 v223, v223, v207
	v_add_f32_e32 v222, v222, v206
	v_add_f32_e32 v221, v221, v205
	v_add_f32_e32 v220, v220, v204
	v_add_f32_e32 v211, v211, v203
	v_add_f32_e32 v210, v210, v202
	v_add_f32_e32 v209, v209, v201
	ds_bpermute_b32 v208, v197, v219
	ds_bpermute_b32 v207, v197, v223
	ds_bpermute_b32 v206, v197, v222
	ds_bpermute_b32 v205, v197, v221
	ds_bpermute_b32 v204, v197, v220
	ds_bpermute_b32 v203, v197, v211
	ds_bpermute_b32 v202, v197, v210
	ds_bpermute_b32 v201, v197, v209
	s_waitcnt lgkmcnt(0)
	v_add_f32_e32 v219, v219, v208
	v_add_f32_e32 v223, v223, v207
	v_add_f32_e32 v222, v222, v206
	v_add_f32_e32 v221, v221, v205
	v_add_f32_e32 v220, v220, v204
	v_add_f32_e32 v211, v211, v203
	v_add_f32_e32 v210, v210, v202
	v_add_f32_e32 v209, v209, v201
	v_fmac_f32_e32 v60, 0xbc800000, v219
	v_fmac_f32_e32 v61, 0xbc800000, v219
	v_fmac_f32_e32 v62, 0xbc800000, v219
	v_fmac_f32_e32 v63, 0xbc800000, v219
	v_mul_f32_e32 v200, v61, v61
	v_fmac_f32_e32 v200, v60, v60
	v_mul_f32_e32 v199, v63, v63
	v_fmac_f32_e32 v199, v62, v62
	v_add_f32_e32 v129, v200, v199
	v_fmac_f32_e32 v92, 0xbc800000, v219
	v_fmac_f32_e32 v93, 0xbc800000, v219
	v_fmac_f32_e32 v94, 0xbc800000, v219
	v_fmac_f32_e32 v95, 0xbc800000, v219
	v_mul_f32_e32 v200, v93, v93
	v_fmac_f32_e32 v200, v92, v92
	v_mul_f32_e32 v199, v95, v95
	v_fmac_f32_e32 v199, v94, v94
	v_add_f32_e32 v200, v200, v199
	v_add_f32_e32 v129, v129, v200
	v_fmac_f32_e32 v120, 0xbc800000, v219
	v_fmac_f32_e32 v121, 0xbc800000, v219
	v_fmac_f32_e32 v122, 0xbc800000, v219
	v_fmac_f32_e32 v123, 0xbc800000, v219
	v_mul_f32_e32 v200, v121, v121
	v_fmac_f32_e32 v200, v120, v120
	v_mul_f32_e32 v199, v123, v123
	v_fmac_f32_e32 v199, v122, v122
	v_add_f32_e32 v200, v200, v199
	v_add_f32_e32 v129, v129, v200
	v_fmac_f32_e32 v124, 0xbc800000, v219
	v_fmac_f32_e32 v125, 0xbc800000, v219
	v_fmac_f32_e32 v126, 0xbc800000, v219
	v_fmac_f32_e32 v127, 0xbc800000, v219
	v_mul_f32_e32 v200, v125, v125
	v_fmac_f32_e32 v200, v124, v124
	v_mul_f32_e32 v199, v127, v127
	v_fmac_f32_e32 v199, v126, v126
	v_add_f32_e32 v200, v200, v199
	v_add_f32_e32 v129, v129, v200
	v_fmac_f32_e32 v56, 0xbc800000, v223
	v_fmac_f32_e32 v57, 0xbc800000, v223
	v_fmac_f32_e32 v58, 0xbc800000, v223
	v_fmac_f32_e32 v59, 0xbc800000, v223
	v_mul_f32_e32 v200, v57, v57
	v_fmac_f32_e32 v200, v56, v56
	v_mul_f32_e32 v199, v59, v59
	v_fmac_f32_e32 v199, v58, v58
	v_add_f32_e32 v131, v200, v199
	v_fmac_f32_e32 v84, 0xbc800000, v223
	v_fmac_f32_e32 v85, 0xbc800000, v223
	v_fmac_f32_e32 v86, 0xbc800000, v223
	v_fmac_f32_e32 v87, 0xbc800000, v223
	v_mul_f32_e32 v200, v85, v85
	v_fmac_f32_e32 v200, v84, v84
	v_mul_f32_e32 v199, v87, v87
	v_fmac_f32_e32 v199, v86, v86
	v_add_f32_e32 v200, v200, v199
	v_add_f32_e32 v131, v131, v200
	v_fmac_f32_e32 v112, 0xbc800000, v223
	v_fmac_f32_e32 v113, 0xbc800000, v223
	v_fmac_f32_e32 v114, 0xbc800000, v223
	v_fmac_f32_e32 v115, 0xbc800000, v223
	v_mul_f32_e32 v200, v113, v113
	v_fmac_f32_e32 v200, v112, v112
	v_mul_f32_e32 v199, v115, v115
	v_fmac_f32_e32 v199, v114, v114
	v_add_f32_e32 v200, v200, v199
	v_add_f32_e32 v131, v131, v200
	v_fmac_f32_e32 v116, 0xbc800000, v223
	v_fmac_f32_e32 v117, 0xbc800000, v223
	v_fmac_f32_e32 v118, 0xbc800000, v223
	v_fmac_f32_e32 v119, 0xbc800000, v223
	v_mul_f32_e32 v200, v117, v117
	v_fmac_f32_e32 v200, v116, v116
	v_mul_f32_e32 v199, v119, v119
	v_fmac_f32_e32 v199, v118, v118
	v_add_f32_e32 v200, v200, v199
	v_add_f32_e32 v131, v131, v200
	v_fmac_f32_e32 v48, 0xbc800000, v222
	v_fmac_f32_e32 v49, 0xbc800000, v222
	v_fmac_f32_e32 v50, 0xbc800000, v222
	v_fmac_f32_e32 v51, 0xbc800000, v222
	v_mul_f32_e32 v200, v49, v49
	v_fmac_f32_e32 v200, v48, v48
	v_mul_f32_e32 v199, v51, v51
	v_fmac_f32_e32 v199, v50, v50
	v_add_f32_e32 v133, v200, v199
	v_fmac_f32_e32 v80, 0xbc800000, v222
	v_fmac_f32_e32 v81, 0xbc800000, v222
	v_fmac_f32_e32 v82, 0xbc800000, v222
	v_fmac_f32_e32 v83, 0xbc800000, v222
	v_mul_f32_e32 v200, v81, v81
	v_fmac_f32_e32 v200, v80, v80
	v_mul_f32_e32 v199, v83, v83
	v_fmac_f32_e32 v199, v82, v82
	v_add_f32_e32 v200, v200, v199
	v_add_f32_e32 v133, v133, v200
	v_fmac_f32_e32 v108, 0xbc800000, v222
	v_fmac_f32_e32 v109, 0xbc800000, v222
	v_fmac_f32_e32 v110, 0xbc800000, v222
	v_fmac_f32_e32 v111, 0xbc800000, v222
	v_mul_f32_e32 v200, v109, v109
	v_fmac_f32_e32 v200, v108, v108
	v_mul_f32_e32 v199, v111, v111
	v_fmac_f32_e32 v199, v110, v110
	v_add_f32_e32 v200, v200, v199
	v_add_f32_e32 v133, v133, v200
	v_fmac_f32_e32 v104, 0xbc800000, v222
	v_fmac_f32_e32 v105, 0xbc800000, v222
	v_fmac_f32_e32 v106, 0xbc800000, v222
	v_fmac_f32_e32 v107, 0xbc800000, v222
	v_mul_f32_e32 v200, v105, v105
	v_fmac_f32_e32 v200, v104, v104
	v_mul_f32_e32 v199, v107, v107
	v_fmac_f32_e32 v199, v106, v106
	v_add_f32_e32 v200, v200, v199
	v_add_f32_e32 v133, v133, v200
	v_fmac_f32_e32 v40, 0xbc800000, v221
	v_fmac_f32_e32 v41, 0xbc800000, v221
	v_fmac_f32_e32 v42, 0xbc800000, v221
	v_fmac_f32_e32 v43, 0xbc800000, v221
	v_mul_f32_e32 v200, v41, v41
	v_fmac_f32_e32 v200, v40, v40
	v_mul_f32_e32 v199, v43, v43
	v_fmac_f32_e32 v199, v42, v42
	v_add_f32_e32 v135, v200, v199
	v_fmac_f32_e32 v72, 0xbc800000, v221
	v_fmac_f32_e32 v73, 0xbc800000, v221
	v_fmac_f32_e32 v74, 0xbc800000, v221
	v_fmac_f32_e32 v75, 0xbc800000, v221
	v_mul_f32_e32 v200, v73, v73
	v_fmac_f32_e32 v200, v72, v72
	v_mul_f32_e32 v199, v75, v75
	v_fmac_f32_e32 v199, v74, v74
	v_add_f32_e32 v200, v200, v199
	v_add_f32_e32 v135, v135, v200
	v_fmac_f32_e32 v100, 0xbc800000, v221
	v_fmac_f32_e32 v101, 0xbc800000, v221
	v_fmac_f32_e32 v102, 0xbc800000, v221
	v_fmac_f32_e32 v103, 0xbc800000, v221
;     __device__ __forceinline__ void operator()(f32x4 (&acc)[2][2][4][2], const Unit& u, int wr, int wc, int fr, int fq) const {
;     ...
;                 for (int bj = 0; bj < 2; ++bj)
; #pragma unroll
;                     for (int n = 0; n < 2; ++n) { const f32x4 d = acc[ai][bj][m][n] - mw; q += (d[0] * d[0] + d[1] * d[1]) + (d[2] * d[2] + d[3] * d[3]); }
;                 q += __shfl_xor(q, 16); q += __shfl_xor(q, 32);
	v_mul_f32_e32 v200, v101, v101
	v_fmac_f32_e32 v200, v100, v100
	v_mul_f32_e32 v199, v103, v103
	v_fmac_f32_e32 v199, v102, v102
	v_add_f32_e32 v200, v200, v199
	v_add_f32_e32 v135, v135, v200
	v_fmac_f32_e32 v96, 0xbc800000, v221
	v_fmac_f32_e32 v97, 0xbc800000, v221
	v_fmac_f32_e32 v98, 0xbc800000, v221
	v_fmac_f32_e32 v99, 0xbc800000, v221
	v_mul_f32_e32 v200, v97, v97
	v_fmac_f32_e32 v200, v96, v96
	v_mul_f32_e32 v199, v99, v99
	v_fmac_f32_e32 v199, v98, v98
	v_add_f32_e32 v200, v200, v199
	v_add_f32_e32 v135, v135, v200
	v_fmac_f32_e32 v88, 0xbc800000, v220
	v_fmac_f32_e32 v89, 0xbc800000, v220
	v_fmac_f32_e32 v90, 0xbc800000, v220
	v_fmac_f32_e32 v91, 0xbc800000, v220
	v_mul_f32_e32 v200, v89, v89
	v_fmac_f32_e32 v200, v88, v88
	v_mul_f32_e32 v199, v91, v91
	v_fmac_f32_e32 v199, v90, v90
	v_add_f32_e32 v143, v200, v199
	v_fmac_f32_e32 v52, 0xbc800000, v220
	v_fmac_f32_e32 v53, 0xbc800000, v220
	v_fmac_f32_e32 v54, 0xbc800000, v220
	v_fmac_f32_e32 v55, 0xbc800000, v220
	v_mul_f32_e32 v200, v53, v53
	v_fmac_f32_e32 v200, v52, v52
	v_mul_f32_e32 v199, v55, v55
	v_fmac_f32_e32 v199, v54, v54
	v_add_f32_e32 v200, v200, v199
	v_add_f32_e32 v143, v143, v200
	v_fmac_f32_e32 v28, 0xbc800000, v220
	v_fmac_f32_e32 v29, 0xbc800000, v220
	v_fmac_f32_e32 v30, 0xbc800000, v220
	v_fmac_f32_e32 v31, 0xbc800000, v220
	v_mul_f32_e32 v200, v29, v29
	v_fmac_f32_e32 v200, v28, v28
	v_mul_f32_e32 v199, v31, v31
	v_fmac_f32_e32 v199, v30, v30
	v_add_f32_e32 v200, v200, v199
	v_add_f32_e32 v143, v143, v200
	v_fmac_f32_e32 v12, 0xbc800000, v220
	v_fmac_f32_e32 v13, 0xbc800000, v220
	v_fmac_f32_e32 v14, 0xbc800000, v220
	v_fmac_f32_e32 v15, 0xbc800000, v220
	v_mul_f32_e32 v200, v13, v13
	v_fmac_f32_e32 v200, v12, v12
	v_mul_f32_e32 v199, v15, v15
	v_fmac_f32_e32 v199, v14, v14
	v_add_f32_e32 v200, v200, v199
	v_add_f32_e32 v143, v143, v200
	v_fmac_f32_e32 v76, 0xbc800000, v211
	v_fmac_f32_e32 v77, 0xbc800000, v211
	v_fmac_f32_e32 v78, 0xbc800000, v211
	v_fmac_f32_e32 v79, 0xbc800000, v211
	v_mul_f32_e32 v200, v77, v77
	v_fmac_f32_e32 v200, v76, v76
	v_mul_f32_e32 v199, v79, v79
	v_fmac_f32_e32 v199, v78, v78
	v_add_f32_e32 v145, v200, v199
	v_fmac_f32_e32 v44, 0xbc800000, v211
	v_fmac_f32_e32 v45, 0xbc800000, v211
	v_fmac_f32_e32 v46, 0xbc800000, v211
	v_fmac_f32_e32 v47, 0xbc800000, v211
	v_mul_f32_e32 v200, v45, v45
	v_fmac_f32_e32 v200, v44, v44
	v_mul_f32_e32 v199, v47, v47
	v_fmac_f32_e32 v199, v46, v46
	v_add_f32_e32 v200, v200, v199
	v_add_f32_e32 v145, v145, v200
	v_fmac_f32_e32 v24, 0xbc800000, v211
	v_fmac_f32_e32 v25, 0xbc800000, v211
	v_fmac_f32_e32 v26, 0xbc800000, v211
	v_fmac_f32_e32 v27, 0xbc800000, v211
	v_mul_f32_e32 v200, v25, v25
	v_fmac_f32_e32 v200, v24, v24
	v_mul_f32_e32 v199, v27, v27
	v_fmac_f32_e32 v199, v26, v26
	v_add_f32_e32 v200, v200, v199
	v_add_f32_e32 v145, v145, v200
	v_fmac_f32_e32 v8, 0xbc800000, v211
	v_fmac_f32_e32 v9, 0xbc800000, v211
	v_fmac_f32_e32 v10, 0xbc800000, v211
	v_fmac_f32_e32 v11, 0xbc800000, v211
	v_mul_f32_e32 v200, v9, v9
	v_fmac_f32_e32 v200, v8, v8
	v_mul_f32_e32 v199, v11, v11
	v_fmac_f32_e32 v199, v10, v10
	v_add_f32_e32 v200, v200, v199
	v_add_f32_e32 v145, v145, v200
	v_fmac_f32_e32 v68, 0xbc800000, v210
	v_fmac_f32_e32 v69, 0xbc800000, v210
	v_fmac_f32_e32 v70, 0xbc800000, v210
	v_fmac_f32_e32 v71, 0xbc800000, v210
	v_mul_f32_e32 v200, v69, v69
	v_fmac_f32_e32 v200, v68, v68
	v_mul_f32_e32 v199, v71, v71
	v_fmac_f32_e32 v199, v70, v70
	v_add_f32_e32 v147, v200, v199
	v_fmac_f32_e32 v36, 0xbc800000, v210
	v_fmac_f32_e32 v37, 0xbc800000, v210
	v_fmac_f32_e32 v38, 0xbc800000, v210
	v_fmac_f32_e32 v39, 0xbc800000, v210
	v_mul_f32_e32 v200, v37, v37
	v_fmac_f32_e32 v200, v36, v36
	v_mul_f32_e32 v199, v39, v39
	v_fmac_f32_e32 v199, v38, v38
	v_add_f32_e32 v200, v200, v199
	v_add_f32_e32 v147, v147, v200
	v_fmac_f32_e32 v20, 0xbc800000, v210
	v_fmac_f32_e32 v21, 0xbc800000, v210
	v_fmac_f32_e32 v22, 0xbc800000, v210
	v_fmac_f32_e32 v23, 0xbc800000, v210
	v_mul_f32_e32 v200, v21, v21
	v_fmac_f32_e32 v200, v20, v20
	v_mul_f32_e32 v199, v23, v23
	v_fmac_f32_e32 v199, v22, v22
	v_add_f32_e32 v200, v200, v199
	v_add_f32_e32 v147, v147, v200
	v_fmac_f32_e32 v4, 0xbc800000, v210
	v_fmac_f32_e32 v5, 0xbc800000, v210
	v_fmac_f32_e32 v6, 0xbc800000, v210
	v_fmac_f32_e32 v7, 0xbc800000, v210
	v_mul_f32_e32 v200, v5, v5
	v_fmac_f32_e32 v200, v4, v4
	v_mul_f32_e32 v199, v7, v7
	v_fmac_f32_e32 v199, v6, v6
	v_add_f32_e32 v200, v200, v199
	v_add_f32_e32 v147, v147, v200
	v_fmac_f32_e32 v64, 0xbc800000, v209
	v_fmac_f32_e32 v65, 0xbc800000, v209
	v_fmac_f32_e32 v66, 0xbc800000, v209
	v_fmac_f32_e32 v67, 0xbc800000, v209
	v_mul_f32_e32 v200, v65, v65
	v_fmac_f32_e32 v200, v64, v64
	v_mul_f32_e32 v199, v67, v67
	v_fmac_f32_e32 v199, v66, v66
	v_add_f32_e32 v149, v200, v199
	v_fmac_f32_e32 v32, 0xbc800000, v209
	v_fmac_f32_e32 v33, 0xbc800000, v209
	v_fmac_f32_e32 v34, 0xbc800000, v209
	v_fmac_f32_e32 v35, 0xbc800000, v209
	v_mul_f32_e32 v200, v33, v33
	v_fmac_f32_e32 v200, v32, v32
	v_mul_f32_e32 v199, v35, v35
	v_fmac_f32_e32 v199, v34, v34
	v_add_f32_e32 v200, v200, v199
	v_add_f32_e32 v149, v149, v200
	v_fmac_f32_e32 v16, 0xbc800000, v209
	v_fmac_f32_e32 v17, 0xbc800000, v209
	v_fmac_f32_e32 v18, 0xbc800000, v209
	v_fmac_f32_e32 v19, 0xbc800000, v209
	v_mul_f32_e32 v200, v17, v17
	v_fmac_f32_e32 v200, v16, v16
	v_mul_f32_e32 v199, v19, v19
	v_fmac_f32_e32 v199, v18, v18
	v_add_f32_e32 v200, v200, v199
	v_add_f32_e32 v149, v149, v200
	v_fmac_f32_e32 v0, 0xbc800000, v209
	v_fmac_f32_e32 v1, 0xbc800000, v209
	v_fmac_f32_e32 v2, 0xbc800000, v209
	v_fmac_f32_e32 v3, 0xbc800000, v209
	v_mul_f32_e32 v200, v1, v1
	v_fmac_f32_e32 v200, v0, v0
	v_mul_f32_e32 v199, v3, v3
	v_fmac_f32_e32 v199, v2, v2
	v_add_f32_e32 v200, v200, v199
	v_add_f32_e32 v149, v149, v200
	ds_bpermute_b32 v208, v198, v129
	ds_bpermute_b32 v207, v198, v131
	ds_bpermute_b32 v206, v198, v133
	ds_bpermute_b32 v205, v198, v135
	ds_bpermute_b32 v204, v198, v143
	ds_bpermute_b32 v203, v198, v145
	ds_bpermute_b32 v202, v198, v147
	ds_bpermute_b32 v201, v198, v149
	s_waitcnt lgkmcnt(0)
;     __device__ __forceinline__ void operator()(f32x4 (&acc)[2][2][4][2], const Unit& u, int wr, int wc, int fr, int fq) const {
;     ...
;                 const float mw = s * (1.0f / 64.0f); float q = 0.f;
; #pragma unroll
;                 for (int bj = 0; bj < 2; ++bj)
; #pragma unroll
;                     for (int n = 0; n < 2; ++n) { const f32x4 d = acc[ai][bj][m][n] - mw; q += (d[0] * d[0] + d[1] * d[1]) + (d[2] * d[2] + d[3] * d[3]); }
;                 q += __shfl_xor(q, 16); q += __shfl_xor(q, 32);
;                 if (fq == 0) P[(ai * HALF + wr * 64 + m * 16 + fr) * 4 + wc] = (f32x2){mw, q};
;             }
;         asm volatile("s_waitcnt lgkmcnt(0)" ::: "memory"); __builtin_amdgcn_s_barrier(); asm volatile("" ::: "memory");
	v_add_f32_e32 v129, v129, v208
	v_add_f32_e32 v131, v131, v207
	v_add_f32_e32 v133, v133, v206
	v_add_f32_e32 v135, v135, v205
	v_add_f32_e32 v143, v143, v204
	v_add_f32_e32 v145, v145, v203
	v_add_f32_e32 v147, v147, v202
	v_add_f32_e32 v149, v149, v201
	ds_bpermute_b32 v208, v197, v129
	ds_bpermute_b32 v207, v197, v131
	ds_bpermute_b32 v206, v197, v133
	ds_bpermute_b32 v205, v197, v135
	ds_bpermute_b32 v204, v197, v143
	ds_bpermute_b32 v203, v197, v145
	ds_bpermute_b32 v202, v197, v147
	ds_bpermute_b32 v201, v197, v149
	s_waitcnt lgkmcnt(0)
	v_add_f32_e32 v129, v129, v208
	v_add_f32_e32 v131, v131, v207
	v_add_f32_e32 v133, v133, v206
	v_add_f32_e32 v135, v135, v205
	v_add_f32_e32 v143, v143, v204
	v_add_f32_e32 v145, v145, v203
	v_add_f32_e32 v147, v147, v202
	v_add_f32_e32 v149, v149, v201
	v_mul_f32_e32 v128, 0x3c800000, v219
	v_mul_f32_e32 v130, 0x3c800000, v223
	v_mul_f32_e32 v132, 0x3c800000, v222
	v_mul_f32_e32 v134, 0x3c800000, v221
	v_mul_f32_e32 v142, 0x3c800000, v220
	v_mul_f32_e32 v144, 0x3c800000, v211
	v_mul_f32_e32 v146, 0x3c800000, v210
	v_mul_f32_e32 v148, 0x3c800000, v209
	s_and_saveexec_b64 s[4:5], s[8:9]
	ds_write_b64 v218, v[128:129]
	ds_write_b64 v218, v[130:131] offset:512
	ds_write_b64 v218, v[132:133] offset:1024
	ds_write_b64 v218, v[134:135] offset:1536
	ds_write_b64 v218, v[142:143] offset:4096
	ds_write_b64 v218, v[144:145] offset:4608
	ds_write_b64 v218, v[146:147] offset:5120
	ds_write_b64 v218, v[148:149] offset:5632
	s_or_b64 exec, exec, s[4:5]
	s_branch .Lres_join_b
